# P2 queue interleave + attn K/V/Q staging loads issued together + ssd_sample head loop unrolled x3 (counted vmcnt, scalar a_log/d_skip)
# speedup vs baseline: 1.0095x; 1.0080x over previous
.LBB0_576:
	s_waitcnt vmcnt(0)
	s_barrier
	s_mov_b64 s[4:5], exec
	v_readlane_b32 s0, v254, 7
	v_readlane_b32 s1, v254, 8
	s_and_b64 s[0:1], s[4:5], s[0:1]
	s_mov_b64 exec, s[0:1]
	v_mov_b32_e32 v0, s76
	ds_write_b32 v0, v152
	s_or_b64 exec, exec, s[4:5]
	s_waitcnt lgkmcnt(0)
	s_barrier
	ds_read_b32 v0, v154
	s_movk_i32 s0, 0x9ff
	s_waitcnt lgkmcnt(0)
	v_cmp_lt_i32_e64 s[4:5], s0, v0
	v_readfirstlane_b32 s89, v0
	s_and_b64 vcc, exec, s[4:5]
	s_cbranch_vccnz .LBB0_575
	s_cmpk_lt_i32 s89, 0x80
	s_cbranch_scc1 .Lq_done
	s_sub_i32 s0, s89, 0x80
	s_mul_i32 s1, s0, 0xd7a
	s_lshr_b32 s1, s1, 16
	s_mul_i32 s3, s1, 19
	s_sub_i32 s0, s0, s3
	s_cmpk_lt_i32 s0, 3
	s_cbranch_scc0 .Lq_a
	s_mul_i32 s1, s1, 3
	s_add_i32 s89, s1, s0
	s_addk_i32 s89, 0x80
	s_branch .Lq_done
.Lq_a:
	s_cmpk_lt_i32 s0, 7
	s_cbranch_scc0 .Lq_b
	s_lshl_b32 s1, s1, 2
	s_add_i32 s89, s1, s0
	s_addk_i32 s89, 0x1fd
	s_branch .Lq_done
.Lq_b:
	s_mul_i32 s1, s1, 12
	s_add_i32 s89, s1, s0
	s_addk_i32 s89, 0x3f9
.Lq_done:
	s_mov_b64 s[6:7], exec
	v_readlane_b32 s0, v254, 7
	v_readlane_b32 s1, v254, 8
	s_and_b64 s[0:1], s[6:7], s[0:1]
	s_mov_b64 exec, s[0:1]
	s_cbranch_execz .LBB0_583
	s_mov_b64 s[10:11], exec
	v_mbcnt_lo_u32_b32 v0, s10, 0
	v_mbcnt_hi_u32_b32 v0, s11, v0
	v_cmp_eq_u32_e32 vcc, 0, v0
	s_and_saveexec_b64 s[8:9], vcc
	s_cbranch_execz .LBB0_582
	s_bcnt1_i32_b64 s0, s[10:11]
	v_mov_b32_e32 v1, s0
	global_atomic_add v1, v73, v1, s[42:43] sc0

.LBB0_583:
	s_or_b64 exec, exec, s[6:7]
	v_mov_b32_e32 v74, v194
	s_mov_b64 s[6:7], -1
	v_readfirstlane_b32 s3, v74
	s_ashr_i32 s86, s3, 6
	v_and_b32_e32 v166, 63, v74
	s_cmpk_gt_i32 s89, 0x7f
	s_cbranch_scc0 .LBB0_663
	s_cmpk_gt_u32 s89, 0x1ff
	s_cbranch_scc0 .LBB0_646
	s_cmpk_gt_u32 s89, 0x3ff
	s_cbranch_scc0 .LBB0_603
	s_add_i32 s2, s89, 0xfffffc00
	s_lshr_b32 s1, s2, 7
	s_mul_i32 s6, s1, 0xab
	s_bfe_u32 s6, s6, 0x70009
	s_mul_i32 s6, s6, 3
	s_sub_i32 s1, s1, s6
	s_and_b32 s1, s1, 0xff
	s_lshl_b32 s16, s1, 1
	s_lshr_b32 s6, 32, s16
	s_and_b32 s17, s89, 31
	s_mul_i32 s2, s2, 0xaaab
	s_add_i32 s6, s6, -1
	s_bfe_u32 s0, s89, 0x20005
	s_lshr_b32 s2, s2, 24
	s_and_b32 s6, s6, s17
	s_cmp_eq_u32 s6, 0
	s_cselect_b64 s[8:9], -1, 0
	s_cmp_lg_u32 s6, 0
	s_mul_i32 s6, s2, 3
	s_cselect_b64 s[10:11], -1, 0
	s_add_i32 s6, s6, s1
	s_lshl_b32 s6, s6, 20
	s_lshl_b32 s7, s0, 18
	s_or_b32 s6, s6, s7
	s_lshl_b32 s18, s6, 1
	s_add_u32 s6, s40, s18
	s_addc_u32 s7, s41, 0
	s_lshl_b32 s12, s17, 14
	s_add_u32 s6, s6, s12
	v_and_b32_e32 v1, 7, v74
	s_addc_u32 s7, s7, 0
	v_lshlrev_b32_e32 v72, 4, v1
	v_lshl_add_u64 v[2:3], s[6:7], 0, v[72:73]
	s_mov_b64 s[12:13], 0x56d2000
	v_lshl_add_u64 v[6:7], v[2:3], 0, s[12:13]
	v_ashrrev_i32_e32 v10, 3, v74
	s_and_b32 s14, s8, 0x4000
	s_add_u32 s20, s6, 0x56d2000
	s_addc_u32 s21, s7, 0
	v_lshlrev_b32_e32 v228, 7, v10
	v_add_u32_e32 v228, v228, v72
	v_lshl_add_u32 v8, v1, 4, 0
	v_add_u32_e32 v229, s14, v228
	v_add_u32_e32 v236, 0x2000, v229
	v_add_u32_e32 v237, 0x4000, v228
	v_add_u32_e32 v238, 0x6000, v228
	global_load_dwordx4 v[196:199], v229, s[20:21]
	global_load_dwordx4 v[200:203], v236, s[20:21]
	global_load_dwordx4 v[204:207], v237, s[20:21]
	global_load_dwordx4 v[208:211], v238, s[20:21]
	v_mad_u64_u32 v[10:11], s[12:13], v10, s79, v[8:9]
	s_lshl_b32 s12, s86, 3
	s_ashr_i32 s13, s12, 31
	s_lshl_b64 s[12:13], s[12:13], 1
	s_add_u32 s6, s6, s12
	s_addc_u32 s7, s7, s13
	s_add_u32 s12, s6, 0x6ed2000
	s_addc_u32 s13, s7, 0
	v_lshlrev_b32_e32 v4, 7, v166
	v_add_u32_e32 v234, s14, v4
	v_add_u32_e32 v239, 0x2000, v234
	v_or_b32_e32 v235, 0x4000, v4
	v_or_b32_e32 v240, 0x6000, v4
	global_load_dwordx4 v[212:215], v234, s[12:13]
	global_load_dwordx4 v[216:219], v239, s[12:13]
	global_load_dwordx4 v[220:223], v235, s[12:13]
	global_load_dwordx4 v[224:227], v240, s[12:13]
	s_mul_i32 s10, s86, 0x1080
	s_add_i32 s10, s10, 0
	v_lshl_add_u32 v12, v166, 1, s10
	s_lshr_b32 s10, 0x1000, s16
	v_readlane_b32 s6, v254, 29
	s_nop 0
	s_add_u32 s12, s6, s18
	v_readlane_b32 s6, v254, 31
	s_nop 0
	s_addc_u32 s13, s6, 0
	s_lshl_b32 s11, s17, 7
	s_lshl_b32 s6, s86, 4
	v_and_b32_e32 v20, 15, v74
	s_add_i32 s7, s6, s11
	v_or_b32_e32 v2, s7, v20
	v_ashrrev_i32_e32 v3, 31, v2
	v_lshlrev_b64 v[2:3], 7, v[2:3]
	v_and_b32_e32 v0, 48, v166
	v_mov_b32_e32 v1, v73
	v_lshl_add_u64 v[2:3], s[12:13], 0, v[2:3]
	v_lshl_add_u64 v[0:1], v[2:3], 0, v[0:1]
	global_load_dwordx4 v[4:7], v[0:1], off
	s_nop 0
	global_load_dwordx4 v[0:3], v[0:1], off offset:64
	s_min_i32 s14, s86, 6
	s_lshl_b32 s7, s14, 4
	v_or_b32_e32 v8, s7, v20
	v_and_b32_e32 v21, 48, v74
	v_mul_lo_u32 v8, v8, s79
	v_add3_u32 v30, 0, v8, v21
	s_add_i32 s21, s7, 16
	v_or_b32_e32 v13, s21, v20
	s_add_i32 s13, s14, 2
	s_lshl_b32 s20, s13, 4
	s_add_i32 s19, s7, 48
	s_add_i32 s12, s14, 4
	s_lshl_b32 s18, s12, 4
	v_or_b32_e32 v26, s18, v20
	v_mul_lo_u32 v26, v26, s79
	v_add3_u32 v42, 0, v26, v21
	s_add_i32 s26, s7, 0x50
	s_add_i32 s15, s14, 6
	s_lshl_b32 s25, s15, 4
	s_add_i32 s24, s7, 0x70
	s_add_i32 s17, s14, 8
	s_lshl_b32 s23, s17, 4
	s_add_i32 s22, s7, 0x90
	s_add_i32 s10, s10, -1
	s_lshl_b32 s70, s2, 12
	s_movk_i32 s2, 0xc00
	s_barrier
	s_waitcnt vmcnt(6)
	s_and_b64 vcc, exec, s[8:9]
	s_cbranch_vccz .Lattn_kz
	v_mov_b32_e32 v196, 0
	v_mov_b32_e32 v197, 0
	v_mov_b32_e32 v198, 0
	v_mov_b32_e32 v199, 0
	v_mov_b32_e32 v200, 0
	v_mov_b32_e32 v201, 0
	v_mov_b32_e32 v202, 0
	v_mov_b32_e32 v203, 0
.Lattn_kz:
	ds_write_b128 v10, v[196:199]
	ds_write_b128 v10, v[200:203] offset:9216
	ds_write_b128 v10, v[204:207] offset:18432
	ds_write_b128 v10, v[208:211] offset:27648
	s_waitcnt vmcnt(2)
	s_cbranch_vccz .Lattn_vz
	v_mov_b32_e32 v212, 0
	v_mov_b32_e32 v213, 0
	v_mov_b32_e32 v214, 0
	v_mov_b32_e32 v215, 0
	v_mov_b32_e32 v216, 0
	v_mov_b32_e32 v217, 0
	v_mov_b32_e32 v218, 0
	v_mov_b32_e32 v219, 0
.Lattn_vz:
	ds_write_b16 v12, v212 offset:36864
	ds_write_b16_d16_hi v12, v212 offset:37392
	ds_write_b16 v12, v213 offset:37920
	ds_write_b16_d16_hi v12, v213 offset:38448
	ds_write_b16 v12, v214 offset:38976
	ds_write_b16_d16_hi v12, v214 offset:39504
	ds_write_b16 v12, v215 offset:40032
	ds_write_b16_d16_hi v12, v215 offset:40560
	ds_write_b16 v12, v216 offset:36992
	ds_write_b16_d16_hi v12, v216 offset:37520
	ds_write_b16 v12, v217 offset:38048
	ds_write_b16_d16_hi v12, v217 offset:38576
	ds_write_b16 v12, v218 offset:39104
	ds_write_b16_d16_hi v12, v218 offset:39632
	ds_write_b16 v12, v219 offset:40160
	ds_write_b16_d16_hi v12, v219 offset:40688
	ds_write_b16 v12, v220 offset:37120
	ds_write_b16_d16_hi v12, v220 offset:37648
	ds_write_b16 v12, v221 offset:38176
	ds_write_b16_d16_hi v12, v221 offset:38704
	ds_write_b16 v12, v222 offset:39232
	ds_write_b16_d16_hi v12, v222 offset:39760
	ds_write_b16 v12, v223 offset:40288
	ds_write_b16_d16_hi v12, v223 offset:40816
	ds_write_b16 v12, v224 offset:37248
	ds_write_b16_d16_hi v12, v224 offset:37776
	ds_write_b16 v12, v225 offset:38304
	ds_write_b16_d16_hi v12, v225 offset:38832
	ds_write_b16 v12, v226 offset:39360
	ds_write_b16_d16_hi v12, v226 offset:39888
	ds_write_b16 v12, v227 offset:40416
	ds_write_b16_d16_hi v12, v227 offset:40944
	s_waitcnt lgkmcnt(0)
	s_barrier
	ds_read_b128 v[8:11], v30
	v_mul_lo_u32 v12, v13, s79
	v_add3_u32 v34, 0, v12, v21
	ds_read_b128 v[12:15], v34
	ds_read_b128 v[30:33], v30 offset:64
	ds_read_b128 v[34:37], v34 offset:64
	v_or_b32_e32 v16, s20, v20
	v_mul_lo_u32 v16, v16, s79
	v_add3_u32 v38, 0, v16, v21
	ds_read_b128 v[16:19], v38
	s_waitcnt vmcnt(1) lgkmcnt(4)
	v_mfma_f32_16x16x32_bf16 v[8:11], v[8:11], v[4:7], 0
	v_or_b32_e32 v22, s19, v20
	v_mul_lo_u32 v22, v22, s79
	v_add3_u32 v39, 0, v22, v21
	s_waitcnt vmcnt(0) lgkmcnt(2)
	v_mfma_f32_16x16x32_bf16 v[30:33], v[30:33], v[0:3], v[8:11]
	ds_read_b128 v[22:25], v39
	ds_read_b128 v[26:29], v42
	s_nop 0
	ds_read_b128 v[8:11], v38 offset:64
	v_mfma_f32_16x16x32_bf16 v[12:15], v[12:15], v[4:7], 0
	s_waitcnt lgkmcnt(3)
	v_mfma_f32_16x16x32_bf16 v[16:19], v[16:19], v[4:7], 0
	v_mfma_f32_16x16x32_bf16 v[34:37], v[34:37], v[0:3], v[12:15]
	s_nop 4
	ds_read_b128 v[12:15], v39 offset:64
	s_waitcnt lgkmcnt(1)
	v_mfma_f32_16x16x32_bf16 v[38:41], v[8:11], v[0:3], v[16:19]
	ds_read_b128 v[8:11], v42 offset:64
	v_mfma_f32_16x16x32_bf16 v[22:25], v[22:25], v[4:7], 0
	s_nop 0
	v_or_b32_e32 v16, s25, v20
	v_mul_lo_u32 v16, v16, s79
	v_add3_u32 v46, 0, v16, v21
	v_mfma_f32_16x16x32_bf16 v[26:29], v[26:29], v[4:7], 0
	s_waitcnt lgkmcnt(1)
	v_mfma_f32_16x16x32_bf16 v[22:25], v[12:15], v[0:3], v[22:25]
	v_or_b32_e32 v12, s26, v20
	v_mul_lo_u32 v12, v12, s79
	v_add3_u32 v12, 0, v12, v21
	s_waitcnt lgkmcnt(0)
	v_mfma_f32_16x16x32_bf16 v[26:29], v[8:11], v[0:3], v[26:29]
	ds_read_b128 v[8:11], v12
	ds_read_b128 v[12:15], v12 offset:64
	ds_read_b128 v[16:19], v46
	s_waitcnt lgkmcnt(2)
	v_mfma_f32_16x16x32_bf16 v[8:11], v[8:11], v[4:7], 0
	s_waitcnt lgkmcnt(1)
	v_mfma_f32_16x16x32_bf16 v[42:45], v[12:15], v[0:3], v[8:11]
	s_nop 5
	ds_read_b128 v[8:11], v46 offset:64
	s_waitcnt lgkmcnt(1)
	v_mfma_f32_16x16x32_bf16 v[12:15], v[16:19], v[4:7], 0
	v_or_b32_e32 v16, s24, v20
	v_mul_lo_u32 v16, v16, s79
	v_add3_u32 v46, 0, v16, v21
	s_waitcnt lgkmcnt(0)
	v_mfma_f32_16x16x32_bf16 v[16:19], v[8:11], v[0:3], v[12:15]
	ds_read_b128 v[8:11], v46
	s_nop 1
	ds_read_b128 v[12:15], v46 offset:64
	v_or_b32_e32 v46, s23, v20
	v_mul_lo_u32 v46, v46, s79
	v_add3_u32 v50, 0, v46, v21
	s_waitcnt lgkmcnt(1)
	v_mfma_f32_16x16x32_bf16 v[8:11], v[8:11], v[4:7], 0
	ds_read_b128 v[46:49], v50
	s_waitcnt lgkmcnt(1)
	v_mfma_f32_16x16x32_bf16 v[12:15], v[12:15], v[0:3], v[8:11]
	s_nop 4
	ds_read_b128 v[8:11], v50 offset:64
	s_waitcnt lgkmcnt(1)
	v_mfma_f32_16x16x32_bf16 v[46:49], v[46:49], v[4:7], 0
	v_or_b32_e32 v50, s22, v20
	v_mul_lo_u32 v50, v50, s79
	v_add3_u32 v21, 0, v50, v21
	s_waitcnt lgkmcnt(0)
	v_mfma_f32_16x16x32_bf16 v[8:11], v[8:11], v[0:3], v[46:49]
	s_nop 2
	ds_read_b128 v[46:49], v21
	ds_read_b128 v[50:53], v21 offset:64
	s_waitcnt lgkmcnt(1)
	v_mfma_f32_16x16x32_bf16 v[46:49], v[46:49], v[4:7], 0
	v_lshrrev_b32_e32 v5, 4, v166
	v_or_b32_e32 v4, s6, v20
	v_lshlrev_b32_e32 v6, 2, v5
	v_add_u32_e32 v7, 0x80, v4
	v_or_b32_e32 v21, s7, v6
	s_waitcnt lgkmcnt(0)
	v_mfma_f32_16x16x32_bf16 v[0:3], v[50:53], v[0:3], v[46:49]
	v_cmp_gt_i32_e64 s[6:7], s62, v21
	s_and_b64 s[6:7], s[8:9], s[6:7]
	v_lshlrev_b32_e32 v72, 3, v5
	v_sub_u32_e32 v46, v7, v21
	v_cmp_lt_u32_e32 vcc, s62, v46
	v_or_b32_e32 v46, 1, v21
	s_or_b64 vcc, vcc, s[6:7]
	v_sub_u32_e32 v47, v7, v46
	v_cmp_gt_i32_e64 s[6:7], s62, v46
	v_cndmask_b32_e32 v30, v30, v156, vcc
	v_cmp_lt_u32_e32 vcc, s62, v47
	s_and_b64 s[6:7], s[8:9], s[6:7]
	s_or_b64 vcc, vcc, s[6:7]
	v_cndmask_b32_e32 v31, v31, v156, vcc
	s_mov_b32 s6, 0xf149f2ca
	v_or_b32_e32 v47, 2, v21
	v_max3_f32 v46, v30, s6, v31
	v_sub_u32_e32 v48, v7, v47
	v_cmp_gt_i32_e64 s[6:7], s62, v47
	v_cmp_lt_u32_e32 vcc, s62, v48
	s_and_b64 s[6:7], s[8:9], s[6:7]
	v_or_b32_e32 v21, 3, v21
	s_or_b64 vcc, vcc, s[6:7]
	v_sub_u32_e32 v47, v7, v21
	v_cmp_gt_i32_e64 s[6:7], s62, v21
	v_cndmask_b32_e32 v32, v32, v156, vcc
	v_cmp_lt_u32_e32 vcc, s62, v47
	s_and_b64 s[6:7], s[8:9], s[6:7]
	s_or_b64 vcc, vcc, s[6:7]
	v_cndmask_b32_e32 v21, v33, v156, vcc
	v_max3_f32 v33, v46, v32, v21
	v_or_b32_e32 v46, s21, v6
	v_sub_u32_e32 v47, v7, v46
	v_cmp_gt_i32_e64 s[6:7], s62, v46
	v_cmp_lt_u32_e32 vcc, s62, v47
	s_and_b64 s[6:7], s[8:9], s[6:7]
	v_or_b32_e32 v47, 1, v46
	s_or_b64 vcc, vcc, s[6:7]
	v_sub_u32_e32 v48, v7, v47
	v_cmp_gt_i32_e64 s[6:7], s62, v47
	v_cndmask_b32_e32 v34, v34, v156, vcc
	v_cmp_lt_u32_e32 vcc, s62, v48
	s_and_b64 s[6:7], s[8:9], s[6:7]
	v_or_b32_e32 v47, 2, v46
	s_or_b64 vcc, vcc, s[6:7]
	v_sub_u32_e32 v48, v7, v47
	v_cmp_gt_i32_e64 s[6:7], s62, v47
	v_cndmask_b32_e32 v35, v35, v156, vcc
	v_cmp_lt_u32_e32 vcc, s62, v48
	s_and_b64 s[6:7], s[8:9], s[6:7]
	v_or_b32_e32 v46, 3, v46
	s_or_b64 vcc, vcc, s[6:7]
	v_sub_u32_e32 v47, v7, v46
	v_cmp_gt_i32_e64 s[6:7], s62, v46
	v_cndmask_b32_e32 v36, v36, v156, vcc
	v_cmp_lt_u32_e32 vcc, s62, v47
	s_and_b64 s[6:7], s[8:9], s[6:7]
	v_or_b32_e32 v46, s20, v6
	s_or_b64 vcc, vcc, s[6:7]
	v_sub_u32_e32 v47, v7, v46
	v_cmp_gt_i32_e64 s[6:7], s62, v46
	v_cndmask_b32_e32 v37, v37, v156, vcc
	v_cmp_lt_u32_e32 vcc, s62, v47
	s_and_b64 s[6:7], s[8:9], s[6:7]
	v_or_b32_e32 v47, 1, v46
	s_or_b64 vcc, vcc, s[6:7]
	v_sub_u32_e32 v48, v7, v47
	v_cmp_gt_i32_e64 s[6:7], s62, v47
	v_cndmask_b32_e32 v38, v38, v156, vcc
	v_cmp_lt_u32_e32 vcc, s62, v48
	s_and_b64 s[6:7], s[8:9], s[6:7]
	v_or_b32_e32 v47, 2, v46
	s_or_b64 vcc, vcc, s[6:7]
	v_sub_u32_e32 v48, v7, v47
	v_cmp_gt_i32_e64 s[6:7], s62, v47
	v_cndmask_b32_e32 v39, v39, v156, vcc
	v_cmp_lt_u32_e32 vcc, s62, v48
	s_and_b64 s[6:7], s[8:9], s[6:7]
	v_or_b32_e32 v46, 3, v46
	s_or_b64 vcc, vcc, s[6:7]
	v_sub_u32_e32 v47, v7, v46
	v_cmp_gt_i32_e64 s[6:7], s62, v46
	v_cndmask_b32_e32 v40, v40, v156, vcc
	v_cmp_lt_u32_e32 vcc, s62, v47
	s_and_b64 s[6:7], s[8:9], s[6:7]
	v_or_b32_e32 v46, s19, v6
	s_or_b64 vcc, vcc, s[6:7]
	v_sub_u32_e32 v47, v7, v46
	v_cmp_gt_i32_e64 s[6:7], s62, v46
	v_cndmask_b32_e32 v41, v41, v156, vcc
	v_cmp_lt_u32_e32 vcc, s62, v47
	s_and_b64 s[6:7], s[8:9], s[6:7]
	v_or_b32_e32 v47, 1, v46
	s_or_b64 vcc, vcc, s[6:7]
	v_sub_u32_e32 v48, v7, v47
	v_cmp_gt_i32_e64 s[6:7], s62, v47
	v_cndmask_b32_e32 v22, v22, v156, vcc
	v_cmp_lt_u32_e32 vcc, s62, v48
	s_and_b64 s[6:7], s[8:9], s[6:7]
	v_or_b32_e32 v47, 2, v46
	s_or_b64 vcc, vcc, s[6:7]
	v_sub_u32_e32 v48, v7, v47
	v_cmp_gt_i32_e64 s[6:7], s62, v47
	v_cndmask_b32_e32 v23, v23, v156, vcc
	v_cmp_lt_u32_e32 vcc, s62, v48
	s_and_b64 s[6:7], s[8:9], s[6:7]
	v_or_b32_e32 v46, 3, v46
	s_or_b64 vcc, vcc, s[6:7]
	v_sub_u32_e32 v47, v7, v46
	v_cmp_gt_i32_e64 s[6:7], s62, v46
	v_cndmask_b32_e32 v24, v24, v156, vcc
	v_cmp_lt_u32_e32 vcc, s62, v47
	s_and_b64 s[6:7], s[8:9], s[6:7]
	v_or_b32_e32 v46, s18, v6
	s_or_b64 vcc, vcc, s[6:7]
	v_sub_u32_e32 v47, v7, v46
	v_cmp_gt_i32_e64 s[6:7], s62, v46
	v_cndmask_b32_e32 v25, v25, v156, vcc
	v_cmp_lt_u32_e32 vcc, s62, v47
	s_and_b64 s[6:7], s[8:9], s[6:7]
	v_or_b32_e32 v47, 1, v46
	s_or_b64 vcc, vcc, s[6:7]
	v_sub_u32_e32 v48, v7, v47
	v_cmp_gt_i32_e64 s[6:7], s62, v47
	v_cndmask_b32_e32 v26, v26, v156, vcc
	v_cmp_lt_u32_e32 vcc, s62, v48
	s_and_b64 s[6:7], s[8:9], s[6:7]
	v_or_b32_e32 v47, 2, v46
	s_or_b64 vcc, vcc, s[6:7]
	v_sub_u32_e32 v48, v7, v47
	v_cmp_gt_i32_e64 s[6:7], s62, v47
	v_cndmask_b32_e32 v27, v27, v156, vcc
	v_cmp_lt_u32_e32 vcc, s62, v48
	s_and_b64 s[6:7], s[8:9], s[6:7]
	v_or_b32_e32 v46, 3, v46
	s_or_b64 vcc, vcc, s[6:7]
	v_sub_u32_e32 v47, v7, v46
	v_cmp_gt_i32_e64 s[6:7], s62, v46
	v_cndmask_b32_e32 v28, v28, v156, vcc
	v_cmp_lt_u32_e32 vcc, s62, v47
	s_and_b64 s[6:7], s[8:9], s[6:7]
	v_or_b32_e32 v46, s26, v6
	s_or_b64 vcc, vcc, s[6:7]
	v_sub_u32_e32 v47, v7, v46
	v_cmp_gt_i32_e64 s[6:7], s62, v46
	v_cndmask_b32_e32 v29, v29, v156, vcc
	v_cmp_lt_u32_e32 vcc, s62, v47
	s_and_b64 s[6:7], s[8:9], s[6:7]
	v_or_b32_e32 v47, 1, v46
	s_or_b64 vcc, vcc, s[6:7]
	v_sub_u32_e32 v48, v7, v47
	v_cmp_gt_i32_e64 s[6:7], s62, v47
	v_cndmask_b32_e32 v42, v42, v156, vcc
	v_cmp_lt_u32_e32 vcc, s62, v48
	s_and_b64 s[6:7], s[8:9], s[6:7]
	v_or_b32_e32 v47, 2, v46
	s_or_b64 vcc, vcc, s[6:7]
	v_sub_u32_e32 v48, v7, v47
	v_cmp_gt_i32_e64 s[6:7], s62, v47
	v_cndmask_b32_e32 v43, v43, v156, vcc
	v_cmp_lt_u32_e32 vcc, s62, v48
	s_and_b64 s[6:7], s[8:9], s[6:7]
	v_or_b32_e32 v46, 3, v46
	s_or_b64 vcc, vcc, s[6:7]
	v_sub_u32_e32 v47, v7, v46
	v_cmp_gt_i32_e64 s[6:7], s62, v46
	v_cndmask_b32_e32 v44, v44, v156, vcc
	v_cmp_lt_u32_e32 vcc, s62, v47
	s_and_b64 s[6:7], s[8:9], s[6:7]
	v_or_b32_e32 v46, s25, v6
	s_or_b64 vcc, vcc, s[6:7]
	v_sub_u32_e32 v47, v7, v46
	v_cmp_gt_i32_e64 s[6:7], s62, v46
	v_cndmask_b32_e32 v45, v45, v156, vcc
	v_cmp_lt_u32_e32 vcc, s62, v47
	s_and_b64 s[6:7], s[8:9], s[6:7]
	v_or_b32_e32 v47, 1, v46
	s_or_b64 vcc, vcc, s[6:7]
	v_sub_u32_e32 v48, v7, v47
	v_cmp_gt_i32_e64 s[6:7], s62, v47
	v_cndmask_b32_e32 v16, v16, v156, vcc
	v_cmp_lt_u32_e32 vcc, s62, v48
	s_and_b64 s[6:7], s[8:9], s[6:7]
	v_or_b32_e32 v47, 2, v46
	s_or_b64 vcc, vcc, s[6:7]
	v_sub_u32_e32 v48, v7, v47
	v_cmp_gt_i32_e64 s[6:7], s62, v47
	v_cndmask_b32_e32 v17, v17, v156, vcc
	v_cmp_lt_u32_e32 vcc, s62, v48
	s_and_b64 s[6:7], s[8:9], s[6:7]
	v_or_b32_e32 v46, 3, v46
	s_or_b64 vcc, vcc, s[6:7]
	v_sub_u32_e32 v47, v7, v46
	v_cmp_gt_i32_e64 s[6:7], s62, v46
	v_cndmask_b32_e32 v18, v18, v156, vcc
	v_cmp_lt_u32_e32 vcc, s62, v47
	s_and_b64 s[6:7], s[8:9], s[6:7]
	v_or_b32_e32 v46, s24, v6
	s_or_b64 vcc, vcc, s[6:7]
	v_sub_u32_e32 v47, v7, v46
	v_cmp_gt_i32_e64 s[6:7], s62, v46
	v_cndmask_b32_e32 v19, v19, v156, vcc
	v_cmp_lt_u32_e32 vcc, s62, v47
	s_and_b64 s[6:7], s[8:9], s[6:7]
	v_or_b32_e32 v47, 1, v46
	s_or_b64 vcc, vcc, s[6:7]
	v_sub_u32_e32 v48, v7, v47
	v_cmp_gt_i32_e64 s[6:7], s62, v47
	v_cndmask_b32_e32 v12, v12, v156, vcc
	v_cmp_lt_u32_e32 vcc, s62, v48
	s_and_b64 s[6:7], s[8:9], s[6:7]
	v_or_b32_e32 v47, 2, v46
	s_or_b64 vcc, vcc, s[6:7]
	v_sub_u32_e32 v48, v7, v47
	v_cmp_gt_i32_e64 s[6:7], s62, v47
	v_cndmask_b32_e32 v13, v13, v156, vcc
	v_cmp_lt_u32_e32 vcc, s62, v48
	s_and_b64 s[6:7], s[8:9], s[6:7]
	v_or_b32_e32 v46, 3, v46
	s_or_b64 vcc, vcc, s[6:7]
	v_sub_u32_e32 v47, v7, v46
	v_cmp_gt_i32_e64 s[6:7], s62, v46
	v_cndmask_b32_e32 v14, v14, v156, vcc
	v_cmp_lt_u32_e32 vcc, s62, v47
	s_and_b64 s[6:7], s[8:9], s[6:7]
	v_or_b32_e32 v46, s23, v6
	s_or_b64 vcc, vcc, s[6:7]
	v_sub_u32_e32 v47, v7, v46
	v_cmp_gt_i32_e64 s[6:7], s62, v46
	v_cndmask_b32_e32 v15, v15, v156, vcc
	v_cmp_lt_u32_e32 vcc, s62, v47
	s_and_b64 s[6:7], s[8:9], s[6:7]
	v_or_b32_e32 v47, 1, v46
	s_or_b64 vcc, vcc, s[6:7]
	v_sub_u32_e32 v48, v7, v47
	v_cmp_gt_i32_e64 s[6:7], s62, v47
	v_cndmask_b32_e32 v8, v8, v156, vcc
	v_cmp_lt_u32_e32 vcc, s62, v48
	s_and_b64 s[6:7], s[8:9], s[6:7]
	v_or_b32_e32 v47, 2, v46
	v_max3_f32 v33, v33, v34, v35
	s_or_b64 vcc, vcc, s[6:7]
	v_sub_u32_e32 v48, v7, v47
	v_cmp_gt_i32_e64 s[6:7], s62, v47
	v_max3_f32 v33, v33, v36, v37
	v_cndmask_b32_e32 v9, v9, v156, vcc
	v_cmp_lt_u32_e32 vcc, s62, v48
	s_and_b64 s[6:7], s[8:9], s[6:7]
	v_or_b32_e32 v46, 3, v46
	v_max3_f32 v33, v33, v38, v39
	s_or_b64 vcc, vcc, s[6:7]
	v_sub_u32_e32 v47, v7, v46
	v_cmp_gt_i32_e64 s[6:7], s62, v46
	v_max3_f32 v33, v33, v40, v41
	v_cndmask_b32_e32 v10, v10, v156, vcc
	v_cmp_lt_u32_e32 vcc, s62, v47
	s_and_b64 s[6:7], s[8:9], s[6:7]
	v_or_b32_e32 v6, s22, v6
	v_max3_f32 v33, v33, v22, v23
	s_or_b64 vcc, vcc, s[6:7]
	v_sub_u32_e32 v46, v7, v6
	v_cmp_gt_i32_e64 s[6:7], s62, v6
	v_max3_f32 v33, v33, v24, v25
	v_cndmask_b32_e32 v11, v11, v156, vcc
	v_cmp_lt_u32_e32 vcc, s62, v46
	s_and_b64 s[6:7], s[8:9], s[6:7]
	v_or_b32_e32 v46, 1, v6
	v_max3_f32 v33, v33, v26, v27
	s_or_b64 vcc, vcc, s[6:7]
	v_sub_u32_e32 v47, v7, v46
	v_cmp_gt_i32_e64 s[6:7], s62, v46
	v_max3_f32 v33, v33, v28, v29
	v_cndmask_b32_e32 v0, v0, v156, vcc
	v_cmp_lt_u32_e32 vcc, s62, v47
	s_and_b64 s[6:7], s[8:9], s[6:7]
	v_or_b32_e32 v46, 2, v6
	v_max3_f32 v33, v33, v42, v43
	s_or_b64 vcc, vcc, s[6:7]
	v_sub_u32_e32 v47, v7, v46
	v_cmp_gt_i32_e64 s[6:7], s62, v46
	v_max3_f32 v33, v33, v44, v45
	v_cndmask_b32_e32 v1, v1, v156, vcc
	v_cmp_lt_u32_e32 vcc, s62, v47
	s_and_b64 s[6:7], s[8:9], s[6:7]
	v_max3_f32 v33, v33, v16, v17
	s_or_b64 vcc, vcc, s[6:7]
	v_max3_f32 v33, v33, v18, v19
	v_cndmask_b32_e32 v46, v2, v156, vcc
	v_or_b32_e32 v2, 3, v6
	v_max3_f32 v33, v33, v12, v13
	v_sub_u32_e32 v6, v7, v2
	v_cmp_gt_i32_e64 s[6:7], s62, v2
	v_max3_f32 v33, v33, v14, v15
	v_cmp_lt_u32_e32 vcc, s62, v6
	s_and_b64 s[6:7], s[8:9], s[6:7]
	v_and_b32_e32 v7, 64, v157
	v_max3_f32 v33, v33, v8, v9
	s_or_b64 vcc, vcc, s[6:7]
	v_xor_b32_e32 v6, 16, v157
	v_add_u32_e32 v7, 64, v7
	v_max3_f32 v33, v33, v10, v11
	v_cndmask_b32_e32 v3, v3, v156, vcc
	v_cmp_lt_i32_e32 vcc, v6, v7
	v_max3_f32 v33, v33, v0, v1
	v_max3_f32 v2, v33, v46, v3
	v_cndmask_b32_e32 v6, v157, v6, vcc
	v_lshlrev_b32_e32 v6, 2, v6
	ds_bpermute_b32 v33, v6, v2
	v_add_u32_e32 v63, 0, v72
	s_waitcnt lgkmcnt(0)
	v_max_f32_e32 v33, v33, v33
	v_max_f32_e32 v2, v2, v33
	v_xor_b32_e32 v33, 32, v157
	v_cmp_lt_i32_e32 vcc, v33, v7
	s_nop 1
	v_cndmask_b32_e32 v7, v157, v33, vcc
	v_lshlrev_b32_e32 v7, 2, v7
	ds_bpermute_b32 v33, v7, v2
	s_waitcnt lgkmcnt(0)
	v_max_f32_e32 v33, v33, v33
	v_max_f32_e32 v2, v2, v33
	v_sub_f32_e32 v30, v30, v2
	v_cmp_gt_f32_e32 vcc, s63, v30
	v_sub_f32_e32 v31, v31, v2
	v_cmp_gt_f32_e64 s[6:7], s63, v31
	v_cndmask_b32_e32 v33, 0, v158, vcc
	v_add_f32_e32 v30, v30, v33
	v_cndmask_b32_e64 v33, 0, v158, s[6:7]
	v_sub_f32_e32 v32, v32, v2
	v_add_f32_e32 v31, v31, v33
	v_cndmask_b32_e32 v33, 0, v159, vcc
	v_cmp_gt_f32_e32 vcc, s63, v32
	v_sub_f32_e32 v21, v21, v2
	v_sub_f32_e32 v34, v34, v2
	v_cndmask_b32_e32 v47, 0, v158, vcc
	v_add_f32_e32 v32, v32, v47
	v_cndmask_b32_e32 v47, 0, v159, vcc
	v_cmp_gt_f32_e32 vcc, s63, v21
	v_exp_f32_e32 v32, v32
	v_sub_f32_e32 v35, v35, v2
	v_cndmask_b32_e32 v48, 0, v158, vcc
	v_add_f32_e32 v21, v21, v48
	v_exp_f32_e32 v21, v21
	v_ldexp_f32 v32, v32, v47
	v_cndmask_b32_e32 v47, 0, v159, vcc
	v_cmp_gt_f32_e32 vcc, s63, v34
	v_ldexp_f32 v21, v21, v47
	v_sub_f32_e32 v36, v36, v2
	v_cndmask_b32_e32 v47, 0, v158, vcc
	v_add_f32_e32 v34, v34, v47
	v_cndmask_b32_e32 v47, 0, v159, vcc
	v_cmp_gt_f32_e32 vcc, s63, v35
	v_exp_f32_e32 v34, v34
	v_sub_f32_e32 v37, v37, v2
	v_cndmask_b32_e32 v48, 0, v158, vcc
	v_add_f32_e32 v35, v35, v48
	v_exp_f32_e32 v35, v35
	v_ldexp_f32 v34, v34, v47
	v_cndmask_b32_e32 v47, 0, v159, vcc
	v_cmp_gt_f32_e32 vcc, s63, v36
	v_ldexp_f32 v35, v35, v47
	v_sub_f32_e32 v38, v38, v2
	v_cndmask_b32_e32 v47, 0, v158, vcc
	v_add_f32_e32 v36, v36, v47
	v_cndmask_b32_e32 v47, 0, v159, vcc
	v_cmp_gt_f32_e32 vcc, s63, v37
	v_exp_f32_e32 v36, v36
	v_sub_f32_e32 v39, v39, v2
	v_cndmask_b32_e32 v48, 0, v158, vcc
	v_add_f32_e32 v37, v37, v48
	v_exp_f32_e32 v37, v37
	v_ldexp_f32 v36, v36, v47
	v_cndmask_b32_e32 v47, 0, v159, vcc
	v_cmp_gt_f32_e32 vcc, s63, v38
	v_ldexp_f32 v37, v37, v47
	v_exp_f32_e32 v30, v30
	v_cndmask_b32_e32 v47, 0, v158, vcc
	v_add_f32_e32 v38, v38, v47
	v_cndmask_b32_e32 v47, 0, v159, vcc
	v_cmp_gt_f32_e32 vcc, s63, v39
	v_exp_f32_e32 v38, v38
	v_sub_f32_e32 v40, v40, v2
	v_cndmask_b32_e32 v48, 0, v158, vcc
	v_add_f32_e32 v39, v39, v48
	v_exp_f32_e32 v39, v39
	v_exp_f32_e32 v31, v31
	v_ldexp_f32 v38, v38, v47
	v_cndmask_b32_e32 v47, 0, v159, vcc
	v_cmp_gt_f32_e32 vcc, s63, v40
	v_ldexp_f32 v39, v39, v47
	v_sub_f32_e32 v41, v41, v2
	v_cndmask_b32_e32 v47, 0, v158, vcc
	v_add_f32_e32 v40, v40, v47
	v_cndmask_b32_e32 v47, 0, v159, vcc
	v_cmp_gt_f32_e32 vcc, s63, v41
	v_ldexp_f32 v30, v30, v33
	v_cndmask_b32_e64 v33, 0, v159, s[6:7]
	v_cndmask_b32_e32 v48, 0, v158, vcc
	v_ldexp_f32 v31, v31, v33
	v_exp_f32_e32 v40, v40
	v_add_f32_e32 v41, v41, v48
	v_add_f32_e32 v33, v30, v31
	v_exp_f32_e32 v41, v41
	v_add_f32_e32 v33, v32, v33
	v_add_f32_e32 v33, v21, v33
	v_sub_f32_e32 v22, v22, v2
	v_add_f32_e32 v33, v34, v33
	v_ldexp_f32 v40, v40, v47
	v_cndmask_b32_e32 v47, 0, v159, vcc
	v_cmp_gt_f32_e32 vcc, s63, v22
	v_add_f32_e32 v33, v35, v33
	v_ldexp_f32 v41, v41, v47
	v_cndmask_b32_e32 v47, 0, v158, vcc
	v_sub_f32_e32 v23, v23, v2
	v_add_f32_e32 v33, v36, v33
	v_add_f32_e32 v22, v22, v47
	v_cndmask_b32_e32 v47, 0, v159, vcc
	v_cmp_gt_f32_e32 vcc, s63, v23
	v_add_f32_e32 v33, v37, v33
	v_exp_f32_e32 v22, v22
	v_cndmask_b32_e32 v48, 0, v158, vcc
	v_add_f32_e32 v33, v38, v33
	v_add_f32_e32 v23, v23, v48
	v_add_f32_e32 v33, v39, v33
	v_exp_f32_e32 v23, v23
	v_add_f32_e32 v33, v40, v33
	v_add_f32_e32 v33, v41, v33
	v_ldexp_f32 v47, v22, v47
	v_add_f32_e32 v22, v47, v33
	v_cndmask_b32_e32 v33, 0, v159, vcc
	v_ldexp_f32 v33, v23, v33
	v_sub_f32_e32 v23, v24, v2
	v_cmp_gt_f32_e32 vcc, s63, v23
	v_sub_f32_e32 v25, v25, v2
	v_add_f32_e32 v22, v33, v22
	v_cndmask_b32_e32 v24, 0, v158, vcc
	v_add_f32_e32 v23, v23, v24
	v_cndmask_b32_e32 v24, 0, v159, vcc
	v_cmp_gt_f32_e32 vcc, s63, v25
	v_exp_f32_e32 v23, v23
	v_sub_f32_e32 v16, v16, v2
	v_cndmask_b32_e32 v48, 0, v158, vcc
	v_add_f32_e32 v25, v25, v48
	v_exp_f32_e32 v25, v25
	v_ldexp_f32 v48, v23, v24
	v_cndmask_b32_e32 v23, 0, v159, vcc
	v_add_f32_e32 v22, v48, v22
	v_ldexp_f32 v49, v25, v23
	v_sub_f32_e32 v23, v26, v2
	v_cmp_gt_f32_e32 vcc, s63, v23
	v_sub_f32_e32 v25, v27, v2
	v_add_f32_e32 v22, v49, v22
	v_cndmask_b32_e32 v24, 0, v158, vcc
	v_add_f32_e32 v23, v23, v24
	v_cndmask_b32_e32 v24, 0, v159, vcc
	v_cmp_gt_f32_e32 vcc, s63, v25
	v_exp_f32_e32 v23, v23
	v_sub_f32_e32 v17, v17, v2
	v_cndmask_b32_e32 v26, 0, v158, vcc
	v_add_f32_e32 v25, v25, v26
	v_exp_f32_e32 v25, v25
	v_ldexp_f32 v26, v23, v24
	v_cndmask_b32_e32 v23, 0, v159, vcc
	v_add_f32_e32 v22, v26, v22
	v_ldexp_f32 v27, v25, v23
	v_sub_f32_e32 v23, v28, v2
	v_cmp_gt_f32_e32 vcc, s63, v23
	v_sub_f32_e32 v25, v29, v2
	v_add_f32_e32 v22, v27, v22
	v_cndmask_b32_e32 v24, 0, v158, vcc
	v_add_f32_e32 v23, v23, v24
	v_cndmask_b32_e32 v24, 0, v159, vcc
	v_cmp_gt_f32_e32 vcc, s63, v25
	v_exp_f32_e32 v23, v23
	v_sub_f32_e32 v19, v19, v2
	v_cndmask_b32_e32 v28, 0, v158, vcc
	v_add_f32_e32 v25, v25, v28
	v_exp_f32_e32 v25, v25
	v_ldexp_f32 v28, v23, v24
	v_cndmask_b32_e32 v23, 0, v159, vcc
	v_add_f32_e32 v22, v28, v22
	v_ldexp_f32 v29, v25, v23
	v_sub_f32_e32 v23, v42, v2
	v_cmp_gt_f32_e32 vcc, s63, v23
	v_sub_f32_e32 v25, v43, v2
	v_add_f32_e32 v22, v29, v22
	v_cndmask_b32_e32 v24, 0, v158, vcc
	v_add_f32_e32 v23, v23, v24
	v_cndmask_b32_e32 v24, 0, v159, vcc
	v_cmp_gt_f32_e32 vcc, s63, v25
	v_exp_f32_e32 v23, v23
	v_sub_f32_e32 v12, v12, v2
	v_cndmask_b32_e32 v42, 0, v158, vcc
	v_add_f32_e32 v25, v25, v42
	v_exp_f32_e32 v25, v25
	v_ldexp_f32 v42, v23, v24
	v_cndmask_b32_e32 v23, 0, v159, vcc
	v_add_f32_e32 v22, v42, v22
	v_ldexp_f32 v43, v25, v23
	v_sub_f32_e32 v23, v44, v2
	v_cmp_gt_f32_e32 vcc, s63, v23
	v_sub_f32_e32 v25, v45, v2
	v_add_f32_e32 v22, v43, v22
	v_cndmask_b32_e32 v24, 0, v158, vcc
	v_add_f32_e32 v23, v23, v24
	v_cndmask_b32_e32 v24, 0, v159, vcc
	v_cmp_gt_f32_e32 vcc, s63, v25
	v_exp_f32_e32 v23, v23
	v_sub_f32_e32 v13, v13, v2
	v_cndmask_b32_e32 v44, 0, v158, vcc
	v_add_f32_e32 v25, v25, v44
	v_exp_f32_e32 v25, v25
	v_ldexp_f32 v44, v23, v24
	v_cndmask_b32_e32 v23, 0, v159, vcc
	v_cmp_gt_f32_e32 vcc, s63, v16
	v_ldexp_f32 v45, v25, v23
	v_add_f32_e32 v22, v44, v22
	v_cndmask_b32_e32 v23, 0, v158, vcc
	v_add_f32_e32 v16, v16, v23
	v_cndmask_b32_e32 v23, 0, v159, vcc
	v_cmp_gt_f32_e32 vcc, s63, v17
	v_exp_f32_e32 v16, v16
	v_add_f32_e32 v22, v45, v22
	v_cndmask_b32_e32 v24, 0, v158, vcc
	v_add_f32_e32 v17, v17, v24
	v_exp_f32_e32 v17, v17
	v_ldexp_f32 v50, v16, v23
	v_add_f32_e32 v16, v50, v22
	v_cndmask_b32_e32 v22, 0, v159, vcc
	v_ldexp_f32 v51, v17, v22
	v_sub_f32_e32 v17, v18, v2
	v_cmp_gt_f32_e32 vcc, s63, v17
	v_add_f32_e32 v16, v51, v16
	v_sub_f32_e32 v15, v15, v2
	v_cndmask_b32_e32 v18, 0, v158, vcc
	v_add_f32_e32 v17, v17, v18
	v_cndmask_b32_e32 v18, 0, v159, vcc
	v_cmp_gt_f32_e32 vcc, s63, v19
	v_exp_f32_e32 v17, v17
	v_sub_f32_e32 v8, v8, v2
	v_cndmask_b32_e32 v22, 0, v158, vcc
	v_add_f32_e32 v19, v19, v22
	v_exp_f32_e32 v19, v19
	v_ldexp_f32 v52, v17, v18
	v_cndmask_b32_e32 v17, 0, v159, vcc
	v_cmp_gt_f32_e32 vcc, s63, v12
	v_ldexp_f32 v53, v19, v17
	v_add_f32_e32 v16, v52, v16
	v_cndmask_b32_e32 v17, 0, v158, vcc
	v_add_f32_e32 v12, v12, v17
	v_cndmask_b32_e32 v17, 0, v159, vcc
	v_cmp_gt_f32_e32 vcc, s63, v13
	v_exp_f32_e32 v12, v12
	v_add_f32_e32 v16, v53, v16
	v_cndmask_b32_e32 v18, 0, v158, vcc
	v_add_f32_e32 v13, v13, v18
	v_exp_f32_e32 v13, v13
	v_ldexp_f32 v54, v12, v17
	v_add_f32_e32 v12, v54, v16
	v_cndmask_b32_e32 v16, 0, v159, vcc
	v_ldexp_f32 v55, v13, v16
	v_sub_f32_e32 v13, v14, v2
	v_cmp_gt_f32_e32 vcc, s63, v13
	v_sub_f32_e32 v9, v9, v2
	v_add_f32_e32 v12, v55, v12
	v_cndmask_b32_e32 v14, 0, v158, vcc
	v_add_f32_e32 v13, v13, v14
	v_cndmask_b32_e32 v14, 0, v159, vcc
	v_cmp_gt_f32_e32 vcc, s63, v15
	v_exp_f32_e32 v13, v13
	v_sub_f32_e32 v11, v11, v2
	v_cndmask_b32_e32 v16, 0, v158, vcc
	v_add_f32_e32 v15, v15, v16
	v_exp_f32_e32 v15, v15
	v_ldexp_f32 v56, v13, v14
	v_cndmask_b32_e32 v13, 0, v159, vcc
	v_cmp_gt_f32_e32 vcc, s63, v8
	v_ldexp_f32 v57, v15, v13
	v_add_f32_e32 v12, v56, v12
	v_cndmask_b32_e32 v13, 0, v158, vcc
	v_add_f32_e32 v8, v8, v13
	v_cndmask_b32_e32 v13, 0, v159, vcc
	v_cmp_gt_f32_e32 vcc, s63, v9
	v_exp_f32_e32 v8, v8
	v_add_f32_e32 v12, v57, v12
	v_cndmask_b32_e32 v14, 0, v158, vcc
	v_add_f32_e32 v9, v9, v14
	v_exp_f32_e32 v9, v9
	v_ldexp_f32 v58, v8, v13
	v_add_f32_e32 v8, v58, v12
	v_cndmask_b32_e32 v12, 0, v159, vcc
	v_ldexp_f32 v59, v9, v12
	v_sub_f32_e32 v9, v10, v2
	v_cmp_gt_f32_e32 vcc, s63, v9
	v_sub_f32_e32 v0, v0, v2
	v_sub_f32_e32 v1, v1, v2
	v_cndmask_b32_e32 v10, 0, v158, vcc
	v_add_f32_e32 v9, v9, v10
	v_cndmask_b32_e32 v10, 0, v159, vcc
	v_cmp_gt_f32_e32 vcc, s63, v11
	v_exp_f32_e32 v9, v9
	v_sub_f32_e32 v3, v3, v2
	v_cndmask_b32_e32 v12, 0, v158, vcc
	v_add_f32_e32 v11, v11, v12
	v_exp_f32_e32 v11, v11
	v_ldexp_f32 v60, v9, v10
	v_cndmask_b32_e32 v9, 0, v159, vcc
	v_cmp_gt_f32_e32 vcc, s63, v0
	v_ldexp_f32 v61, v11, v9
	v_add_f32_e32 v8, v59, v8
	v_cndmask_b32_e32 v9, 0, v158, vcc
	v_add_f32_e32 v0, v0, v9
	v_cndmask_b32_e32 v9, 0, v159, vcc
	v_cmp_gt_f32_e32 vcc, s63, v1
	v_exp_f32_e32 v0, v0
	v_add_f32_e32 v8, v60, v8
	v_cndmask_b32_e32 v10, 0, v158, vcc
	v_add_f32_e32 v1, v1, v10
	v_exp_f32_e32 v1, v1
	v_ldexp_f32 v0, v0, v9
	v_cndmask_b32_e32 v9, 0, v159, vcc
	v_add_f32_e32 v8, v61, v8
	v_ldexp_f32 v1, v1, v9
	v_sub_f32_e32 v9, v46, v2
	v_cmp_gt_f32_e32 vcc, s63, v9
	v_add_f32_e32 v8, v0, v8
	v_add_f32_e32 v8, v1, v8
	v_cndmask_b32_e32 v10, 0, v158, vcc
	v_add_f32_e32 v9, v9, v10
	v_cndmask_b32_e32 v10, 0, v159, vcc
	v_cmp_gt_f32_e32 vcc, s63, v3
	v_exp_f32_e32 v9, v9
	s_lshl_b32 s6, s14, 5
	v_cndmask_b32_e32 v11, 0, v158, vcc
	v_add_f32_e32 v3, v3, v11
	v_exp_f32_e32 v3, v3
	v_ldexp_f32 v46, v9, v10
	v_cndmask_b32_e32 v9, 0, v159, vcc
	v_add_f32_e32 v8, v46, v8
	v_ldexp_f32 v62, v3, v9
	v_add_f32_e32 v3, v62, v8
	ds_bpermute_b32 v6, v6, v3
	s_movk_i32 s14, 0x210
	v_mad_u32_u24 v64, v20, s14, v63
	v_add_u32_e32 v65, s6, v64
	s_lshl_b32 s7, s13, 5
	s_waitcnt lgkmcnt(0)
	v_add_f32_e32 v3, v3, v6
	ds_bpermute_b32 v5, v7, v3
	v_add_u32_e32 v6, 0x9000, v65
	ds_read2_b64 v[6:9], v6 offset1:4
	v_add_u32_e32 v67, s7, v64
	v_add_u32_e32 v14, 0x9000, v67
	s_waitcnt lgkmcnt(1)
	v_add_f32_e32 v3, v3, v5
	v_div_scale_f32 v5, s[8:9], v3, v3, 1.0
	ds_read2_b64 v[14:17], v14 offset1:4
	s_lshl_b32 s8, s12, 5
	v_add_u32_e32 v68, s8, v64
	v_add_u32_e32 v19, 0x9000, v68
	v_cvt_pk_bf16_f32 v10, v30, v31
	v_cvt_pk_bf16_f32 v11, v32, v21
	v_cvt_pk_bf16_f32 v12, v34, v35
	v_cvt_pk_bf16_f32 v13, v36, v37
	ds_read2_b64 v[22:25], v19 offset1:4
	v_cvt_pk_bf16_f32 v18, v38, v39
	s_waitcnt lgkmcnt(2)
	v_mfma_f32_16x16x32_bf16 v[6:9], v[6:9], v[10:13], 0
	v_cvt_pk_bf16_f32 v19, v40, v41
	v_cvt_pk_bf16_f32 v20, v47, v33
	v_cvt_pk_bf16_f32 v21, v48, v49
	s_lshl_b32 s9, s15, 5
	v_add_u32_e32 v47, s9, v64
	s_waitcnt lgkmcnt(1)
	v_mfma_f32_16x16x32_bf16 v[6:9], v[14:17], v[18:21], v[6:9]
	v_cvt_pk_bf16_f32 v14, v26, v27
	v_cvt_pk_bf16_f32 v15, v28, v29
	v_cvt_pk_bf16_f32 v16, v42, v43
	v_cvt_pk_bf16_f32 v17, v44, v45
	s_lshl_b32 s12, s17, 5
	v_add_u32_e32 v48, s12, v64
	s_waitcnt lgkmcnt(0)
	v_mfma_f32_16x16x32_bf16 v[6:9], v[22:25], v[14:17], v[6:9]
	v_add_u32_e32 v22, 0x9000, v47
	ds_read2_b64 v[22:25], v22 offset1:4
	v_add_u32_e32 v29, 0x9000, v48
	ds_read2_b64 v[30:33], v29 offset1:4
	v_cvt_pk_bf16_f32 v26, v50, v51
	v_cvt_pk_bf16_f32 v27, v52, v53
	v_cvt_pk_bf16_f32 v28, v54, v55
	v_cvt_pk_bf16_f32 v29, v56, v57
	v_rcp_f32_e32 v66, v5
	s_waitcnt lgkmcnt(1)
	v_mfma_f32_16x16x32_bf16 v[6:9], v[22:25], v[26:29], v[6:9]
	v_cvt_pk_bf16_f32 v24, v0, v1
	v_add_u32_e32 v0, 0xb000, v65
	ds_read2_b64 v[34:37], v0 offset0:32 offset1:36
	v_cvt_pk_bf16_f32 v22, v58, v59
	v_cvt_pk_bf16_f32 v23, v60, v61
	v_cvt_pk_bf16_f32 v25, v46, v62
	v_add_u32_e32 v0, 0xb000, v67
	v_add_u32_e32 v1, 0xb000, v68
	s_waitcnt lgkmcnt(1)
	v_mfma_f32_16x16x32_bf16 v[6:9], v[30:33], v[22:25], v[6:9]
	ds_read2_b64 v[30:33], v0 offset0:32 offset1:36
	ds_read2_b64 v[38:41], v1 offset0:32 offset1:36
	v_fma_f32 v0, -v5, v66, 1.0
	s_waitcnt lgkmcnt(2)
	v_mfma_f32_16x16x32_bf16 v[34:37], v[34:37], v[10:13], 0
	v_fmac_f32_e32 v66, v0, v66
	v_add_u32_e32 v0, 0xb000, v47
	v_add_u32_e32 v1, 0xb000, v48
	s_waitcnt lgkmcnt(1)
	v_mfma_f32_16x16x32_bf16 v[30:33], v[30:33], v[18:21], v[34:37]
	ds_read2_b64 v[42:45], v1 offset0:32 offset1:36
	s_nop 1
	ds_read2_b64 v[34:37], v0 offset0:32 offset1:36
	v_div_scale_f32 v0, vcc, 1.0, v3, 1.0
	s_waitcnt lgkmcnt(2)
	v_mfma_f32_16x16x32_bf16 v[30:33], v[38:41], v[14:17], v[30:33]
	v_add_u32_e32 v38, 0xd000, v65
	ds_read2_b64 v[38:41], v38 offset0:64 offset1:68
	v_mul_f32_e32 v1, v0, v66
	s_waitcnt lgkmcnt(1)
	v_mfma_f32_16x16x32_bf16 v[30:33], v[34:37], v[26:29], v[30:33]
	v_add_u32_e32 v34, 0xd000, v67
	ds_read2_b64 v[34:37], v34 offset0:64 offset1:68
	v_fma_f32 v46, -v5, v1, v0
	v_mfma_f32_16x16x32_bf16 v[30:33], v[42:45], v[22:25], v[30:33]
	v_add_u32_e32 v42, 0xd000, v68
	ds_read2_b64 v[42:45], v42 offset0:64 offset1:68
	v_fmac_f32_e32 v1, v46, v66
	s_waitcnt lgkmcnt(2)
	v_mfma_f32_16x16x32_bf16 v[38:41], v[38:41], v[10:13], 0
	v_fma_f32 v0, -v5, v1, v0
	v_div_fmas_f32 v0, v0, v66, v1
	v_add_u32_e32 v1, 0xd000, v47
	s_waitcnt lgkmcnt(1)
	v_mfma_f32_16x16x32_bf16 v[34:37], v[34:37], v[18:21], v[38:41]
	v_div_fixup_f32 v0, v0, v3, 1.0
	v_cmp_gt_u32_e32 vcc, 16, v166
	s_nop 0
	ds_read2_b64 v[38:41], v1 offset0:64 offset1:68
	v_add_u32_e32 v1, 0xd000, v48
	s_waitcnt lgkmcnt(1)
	v_mfma_f32_16x16x32_bf16 v[34:37], v[42:45], v[14:17], v[34:37]
	ds_read2_b64 v[42:45], v1 offset0:64 offset1:68
	v_or_b32_e32 v1, 48, v166
	v_mad_u32_u24 v1, v1, s14, v63
	v_add_u32_e32 v5, s6, v1
	v_add_u32_e32 v5, 0x9000, v5
	ds_read2_b64 v[46:49], v5 offset1:4
	v_add_u32_e32 v5, s7, v1
	v_add_u32_e32 v5, 0x9000, v5
	s_waitcnt lgkmcnt(2)
	v_mfma_f32_16x16x32_bf16 v[34:37], v[38:41], v[26:29], v[34:37]
	ds_read2_b64 v[38:41], v5 offset1:4
	v_add_u32_e32 v5, s8, v1
	v_add_u32_e32 v5, 0x9000, v5
	s_waitcnt lgkmcnt(2)
	v_mfma_f32_16x16x32_bf16 v[34:37], v[42:45], v[22:25], v[34:37]
	ds_read2_b64 v[42:45], v5 offset1:4
	v_add_u32_e32 v5, s9, v1
	v_add_u32_e32 v5, 0x9000, v5
	s_waitcnt lgkmcnt(2)
	v_mfma_f32_16x16x32_bf16 v[10:13], v[46:49], v[10:13], 0
	ds_read2_b64 v[46:49], v5 offset1:4
	v_add_u32_e32 v1, s12, v1
	v_add_u32_e32 v1, 0x9000, v1
	s_waitcnt lgkmcnt(2)
	v_mfma_f32_16x16x32_bf16 v[10:13], v[38:41], v[18:21], v[10:13]
	ds_read2_b64 v[18:21], v1 offset1:4
	v_pk_mul_f32 v[32:33], v[32:33], v[0:1] op_sel_hi:[1,0]
	s_sub_i32 s6, 12, s16
	s_waitcnt lgkmcnt(2)
	v_mfma_f32_16x16x32_bf16 v[10:13], v[42:45], v[14:17], v[10:13]
	v_mul_f32_e64 v14, v8, v0
	v_mul_f32_e64 v15, v9, v0
	v_pk_mul_f32 v[16:17], v[6:7], v[0:1] op_sel_hi:[1,0]
	s_waitcnt lgkmcnt(1)
	v_mfma_f32_16x16x32_bf16 v[6:9], v[46:49], v[26:29], v[10:13]
	v_mul_f32_e64 v26, v34, v0
	v_mul_f32_e64 v27, v35, v0
	v_cvt_pk_bf16_f32 v16, v16, v17
	v_cvt_pk_bf16_f32 v17, v14, v15
	s_waitcnt lgkmcnt(0)
	v_mfma_f32_16x16x32_bf16 v[6:9], v[18:21], v[22:25], v[6:9]
	v_mul_f32_e64 v10, v30, v0
	v_mul_f32_e64 v11, v31, v0
	v_pk_mul_f32 v[12:13], v[36:37], v[0:1] op_sel_hi:[1,0]
	v_cvt_pk_bf16_f32 v10, v10, v11
	v_cvt_pk_bf16_f32 v11, v32, v33
	s_nop 2
	v_pk_mul_f32 v[8:9], v[0:1], v[8:9] op_sel_hi:[0,1]
	v_pk_mul_f32 v[6:7], v[0:1], v[6:7] op_sel_hi:[0,1]
	v_add_u32_e32 v0, s11, v4
	v_ashrrev_i32_e32 v1, s6, v0
	v_and_b32_e32 v0, s10, v0
	v_lshl_add_u32 v0, v0, s16, v1
	v_readlane_b32 s6, v254, 33
	v_ashrrev_i32_e32 v1, 31, v0
	v_readlane_b32 s7, v254, 34
	v_lshl_add_u64 v[0:1], v[0:1], 0, s[70:71]
	s_lshl_b32 s70, s1, 9
	v_mov_b64_e32 v[4:5], s[6:7]
	v_mad_u64_u32 v[4:5], s[6:7], v0, s2, v[4:5]
	v_mad_i32_i24 v5, v1, s2, v5
	v_lshl_add_u64 v[4:5], v[4:5], 0, s[70:71]
	s_lshl_b32 s70, s0, 7
	v_lshl_add_u64 v[4:5], v[4:5], 0, s[70:71]
	v_lshl_add_u64 v[4:5], v[4:5], 0, v[72:73]
	global_store_dwordx2 v[4:5], v[10:11], off offset:32
	v_cvt_pk_bf16_f32 v10, v26, v27
	v_cvt_pk_bf16_f32 v11, v12, v13
	v_cvt_pk_bf16_f32 v6, v6, v7
	v_cvt_pk_bf16_f32 v7, v8, v9
	global_store_dwordx2 v[4:5], v[16:17], off
	global_store_dwordx2 v[4:5], v[10:11], off offset:64
	global_store_dwordx2 v[4:5], v[6:7], off offset:96
	s_and_saveexec_b64 s[6:7], vcc
	s_cbranch_execz .LBB0_602
	v_cmp_gt_f32_e32 vcc, s77, v3
	v_readlane_b32 s8, v254, 35
	v_readlane_b32 s9, v254, 36
	v_cndmask_b32_e64 v4, 0, 32, vcc
	v_ldexp_f32 v3, v3, v4
	v_log_f32_e32 v3, v3
	v_cndmask_b32_e32 v6, 0, v160, vcc
	v_mad_u64_u32 v[4:5], s[8:9], v0, 48, s[8:9]
	v_sub_f32_e32 v0, v3, v6
	v_add_f32_e32 v0, v2, v0
	v_mad_i32_i24 v5, v1, 48, v5
	s_lshl_b32 s70, s1, 4
	v_mul_f32_e32 v2, 0x3f317218, v0
	v_lshl_add_u64 v[0:1], v[4:5], 0, s[70:71]
	s_lshl_b32 s70, s0, 2
	v_lshl_add_u64 v[0:1], v[0:1], 0, s[70:71]
	global_store_dword v[0:1], v2, off

.LBB0_683:
	s_or_b64 exec, exec, s[8:9]
	v_ashrrev_i32_e32 v16, 3, v74
	s_mul_i32 s8, s89, 12
	s_ashr_i32 s9, s8, 31
	v_ashrrev_i32_e32 v17, 31, v16
	s_lshl_b64 s[0:1], s[8:9], 13
	v_lshlrev_b64 v[0:1], 7, v[16:17]
	v_and_b32_e32 v18, 7, v74
	v_lshl_add_u64 v[0:1], v[0:1], 0, s[0:1]
	v_lshl_or_b32 v0, v18, 4, v0
	v_lshl_add_u64 v[0:1], v[0:1], 2, s[50:51]
	s_mov_b64 s[0:1], 0x8000
	v_lshl_add_u64 v[12:13], v[0:1], 0, s[0:1]
	s_mov_b32 s0, 0x8000
	s_waitcnt lgkmcnt(0)
	s_barrier
	global_load_dwordx4 v[32:35], v[0:1], off offset:48 nt
	global_load_dwordx4 v[36:39], v[0:1], off offset:32 nt
	global_load_dwordx4 v[40:43], v[0:1], off offset:16 nt
	global_load_dwordx4 v[44:47], v[0:1], off nt
	v_add_co_u32_e32 v0, vcc, s0, v0
	v_and_b32_e32 v20, 64, v157
	s_nop 0
	v_addc_co_u32_e32 v1, vcc, 0, v1, vcc
	global_load_dwordx4 v[0:3], v[0:1], off nt
	s_nop 0
	global_load_dwordx4 v[4:7], v[12:13], off offset:48 nt
	global_load_dwordx4 v[8:11], v[12:13], off offset:32 nt
	s_nop 0
	global_load_dwordx4 v[12:15], v[12:13], off offset:16 nt
	v_xor_b32_e32 v19, 1, v157
	v_add_u32_e32 v60, 64, v20
	v_cmp_lt_i32_e32 vcc, v19, v60
	v_lshl_add_u32 v64, v16, 2, 0
	s_lshl_b64 s[2:3], s[8:9], 15
	v_cndmask_b32_e32 v19, v157, v19, vcc
	v_lshlrev_b32_e32 v61, 2, v19
	v_xor_b32_e32 v19, 2, v157
	v_cmp_lt_i32_e32 vcc, v19, v60
	v_lshlrev_b64 v[16:17], 9, v[16:17]
	v_cmp_eq_u32_e64 s[6:7], 0, v18
	v_cndmask_b32_e32 v19, v157, v19, vcc
	v_lshlrev_b32_e32 v62, 2, v19
	v_xor_b32_e32 v19, 4, v157
	v_cmp_lt_i32_e32 vcc, v19, v60
	v_lshlrev_b32_e32 v18, 6, v18
	v_lshl_add_u64 v[16:17], s[2:3], 0, v[16:17]
	v_cndmask_b32_e32 v19, v157, v19, vcc
	v_or_b32_e32 v16, v16, v18
	v_lshlrev_b32_e32 v63, 2, v19
	v_add_u32_e32 v65, 0, v18
	v_lshl_add_u64 v[48:49], s[50:51], 0, v[16:17]
	v_lshl_add_u64 v[50:51], s[56:57], 0, v[16:17]
	s_mov_b32 s0, 0
	s_mov_b64 s[8:9], 0
	s_mov_b64 s[10:11], s[46:47]
	s_mov_b64 s[12:13], s[44:45]
	s_mov_b32 s1, s88
	s_branch .Lssd_body0
.Lssd_body0:
	s_cmp_gt_u32 s0, 9
	s_cbranch_scc1 .Lssd0_nopf
	v_lshl_add_u64 v[90:91], v[48:49], 0, s[8:9]
	s_mov_b64 s[2:3], 0x10000
	v_lshl_add_u64 v[90:91], v[90:91], 0, s[2:3]
	global_load_dwordx4 v[16:19], v[90:91], off offset:48 nt
	global_load_dwordx4 v[20:23], v[90:91], off offset:32 nt
	global_load_dwordx4 v[28:31], v[90:91], off offset:16 nt
	global_load_dwordx4 v[24:27], v[90:91], off nt
.Lssd0_nopf:
	s_load_dword s16, s[12:13], 0x0
	s_load_dword s17, s[10:11], 0x0
	s_mul_i32 s2, s0, 0xab
	s_and_b32 s2, s2, 0xfe00
	v_add_u32_e32 v67, s2, v65
	s_cmp_lt_u32 s0, 2
	s_cbranch_scc1 .Lssd0_w8
	s_cmp_gt_u32 s0, 9
	s_cbranch_scc1 .Lssd0_w8
	s_waitcnt vmcnt(16)
	s_branch .Lssd0_wd
.Lssd0_w8:
	s_waitcnt vmcnt(8)
.Lssd0_wd:
	s_waitcnt lgkmcnt(0)
	v_mov_b32_e32 v52, s16
	v_mov_b32_e32 v66, s17
	v_mul_f32_e32 v52, 0x3fb8aa3b, v52
	v_exp_f32_e32 v68, v52
	v_mov_b32_e32 v52, s1
	ds_read_b32 v53, v52
	s_waitcnt lgkmcnt(0)
	v_mul_f32_e64 v52, v53, -v68
	v_mul_f32_e32 v52, 0x3fb8aa3b, v52
	v_exp_f32_e32 v58, v52
	ds_read_b32 v52, v64
	ds_read_b128 v[54:57], v67 offset:3072
	ds_read_b128 v[74:77], v67 offset:3088
	ds_read_b128 v[78:81], v67 offset:3104
	ds_read_b128 v[82:85], v67 offset:3120
	v_pk_mul_f32 v[46:47], v[46:47], v[58:59] op_sel_hi:[1,0]
	v_pk_mul_f32 v[86:87], v[44:45], v[58:59] op_sel_hi:[1,0]
	s_waitcnt lgkmcnt(4)
	v_mul_f32_e32 v70, v53, v52
	s_waitcnt lgkmcnt(3)
	v_pk_fma_f32 v[44:45], v[56:57], v[70:71], v[46:47] op_sel_hi:[1,0,1]
	v_pk_fma_f32 v[46:47], v[54:55], v[70:71], v[86:87] op_sel_hi:[1,0,1]
	ds_read_b128 v[54:57], v67 offset:5120
	v_pk_mul_f32 v[42:43], v[42:43], v[58:59] op_sel_hi:[1,0]
	s_waitcnt lgkmcnt(0)
	v_mul_f32_e32 v53, v55, v47
	v_fmac_f32_e32 v53, v54, v46
	v_mul_f32_e32 v54, v57, v45
	v_fmac_f32_e32 v54, v56, v44
	v_add_f32_e32 v53, v53, v54
	v_pk_mul_f32 v[54:55], v[40:41], v[58:59] op_sel_hi:[1,0]
	v_pk_fma_f32 v[40:41], v[70:71], v[76:77], v[42:43] op_sel_hi:[0,1,1]
	v_pk_fma_f32 v[42:43], v[70:71], v[74:75], v[54:55] op_sel_hi:[0,1,1]
	ds_read_b128 v[54:57], v67 offset:5136
	v_add_f32_e32 v53, 0, v53
	s_waitcnt lgkmcnt(0)
	v_mul_f32_e32 v55, v55, v43
	v_fmac_f32_e32 v55, v54, v42
	v_mul_f32_e32 v54, v57, v41
	v_fmac_f32_e32 v54, v56, v40
	v_add_f32_e32 v54, v55, v54
	v_add_f32_e32 v53, v54, v53
	v_pk_mul_f32 v[54:55], v[70:71], v[78:79] op_sel_hi:[0,1]
	v_pk_mul_f32 v[56:57], v[70:71], v[80:81] op_sel_hi:[0,1]
	v_pk_fma_f32 v[38:39], v[38:39], v[58:59], v[56:57] op_sel_hi:[1,0,1]
	v_pk_fma_f32 v[36:37], v[36:37], v[58:59], v[54:55] op_sel_hi:[1,0,1]
	ds_read_b128 v[54:57], v67 offset:5152
	s_waitcnt lgkmcnt(0)
	v_mul_f32_e32 v55, v55, v37
	v_fmac_f32_e32 v55, v54, v36
	v_mul_f32_e32 v54, v57, v39
	v_fmac_f32_e32 v54, v56, v38
	v_add_f32_e32 v54, v55, v54
	v_add_f32_e32 v53, v54, v53
	v_pk_mul_f32 v[54:55], v[70:71], v[82:83] op_sel_hi:[0,1]
	v_pk_mul_f32 v[56:57], v[70:71], v[84:85] op_sel_hi:[0,1]
	v_pk_fma_f32 v[34:35], v[34:35], v[58:59], v[56:57] op_sel_hi:[1,0,1]
	v_pk_fma_f32 v[32:33], v[32:33], v[58:59], v[54:55] op_sel_hi:[1,0,1]
	ds_read_b128 v[54:57], v67 offset:5168
	s_waitcnt lgkmcnt(0)
	v_mul_f32_e32 v55, v55, v33
	v_fmac_f32_e32 v55, v54, v32
	v_mul_f32_e32 v54, v57, v35
	v_fmac_f32_e32 v54, v56, v34
	v_add_f32_e32 v54, v55, v54
	v_add_f32_e32 v53, v53, v54
	ds_bpermute_b32 v54, v61, v53
	s_waitcnt lgkmcnt(0)
	v_add_f32_e32 v53, v53, v54
	ds_bpermute_b32 v54, v62, v53
	s_waitcnt lgkmcnt(0)
	v_add_f32_e32 v53, v53, v54
	ds_bpermute_b32 v54, v63, v53
	s_and_saveexec_b64 s[14:15], s[6:7]
	s_cbranch_execz .Lssd0_689
	ds_read_b32 v55, v64 offset:41216
	s_waitcnt lgkmcnt(1)
	v_add_f32_e32 v53, v53, v54
	v_fmac_f32_e32 v53, v66, v52
	s_waitcnt lgkmcnt(0)
	v_mul_f32_e32 v56, 0xbfb8aa3b, v55
	v_exp_f32_e32 v56, v56
	s_nop 0
	v_add_f32_e32 v54, 1.0, v56
	v_div_scale_f32 v56, s[2:3], v54, v54, v55
	v_rcp_f32_e32 v57, v56
	v_div_scale_f32 v52, vcc, v55, v54, v55
	v_fma_f32 v58, -v56, v57, 1.0
	v_fmac_f32_e32 v57, v58, v57
	v_mul_f32_e32 v58, v52, v57
	v_fma_f32 v59, -v56, v58, v52
	v_fmac_f32_e32 v58, v59, v57
	v_fma_f32 v52, -v56, v58, v52
	v_div_fmas_f32 v52, v52, v57, v58
	v_div_fixup_f32 v52, v52, v54, v55
	v_mul_f32_e32 v52, v53, v52
	ds_write_b32 v64, v52 offset:28928
.Lssd0_689:
	s_or_b64 exec, exec, s[14:15]
	v_mov_b32_e32 v52, s1
	ds_read_b32 v53, v52 offset:48
	ds_read_b32 v52, v64 offset:7168
	s_waitcnt lgkmcnt(1)
	v_mul_f32_e32 v54, v53, v68
	v_mul_f32_e32 v54, 0xbfb8aa3b, v54
	v_exp_f32_e32 v58, v54
	ds_read_b128 v[54:57], v67 offset:10240
	ds_read_b128 v[74:77], v67 offset:10256
	ds_read_b128 v[78:81], v67 offset:12288
	s_waitcnt lgkmcnt(3)
	v_mul_f32_e32 v70, v53, v52
	ds_read_b128 v[82:85], v67 offset:10272
	ds_read_b128 v[86:89], v67 offset:10288
	v_pk_mul_f32 v[44:45], v[44:45], v[58:59] op_sel_hi:[1,0]
	v_pk_mul_f32 v[46:47], v[46:47], v[58:59] op_sel_hi:[1,0]
	s_waitcnt lgkmcnt(4)
	v_pk_fma_f32 v[44:45], v[56:57], v[70:71], v[44:45] op_sel_hi:[1,0,1]
	v_pk_fma_f32 v[46:47], v[54:55], v[70:71], v[46:47] op_sel_hi:[1,0,1]
	ds_read_b128 v[54:57], v67 offset:12304
	s_waitcnt lgkmcnt(3)
	v_mul_f32_e32 v59, v81, v45
	v_fmac_f32_e32 v59, v80, v44
	v_pk_mul_f32 v[40:41], v[40:41], v[58:59] op_sel_hi:[1,0]
	v_pk_mul_f32 v[42:43], v[42:43], v[58:59] op_sel_hi:[1,0]
	v_pk_fma_f32 v[40:41], v[70:71], v[76:77], v[40:41] op_sel_hi:[0,1,1]
	v_pk_fma_f32 v[42:43], v[70:71], v[74:75], v[42:43] op_sel_hi:[0,1,1]
	s_waitcnt lgkmcnt(2)
	v_pk_mul_f32 v[74:75], v[70:71], v[84:85] op_sel_hi:[0,1]
	v_pk_mul_f32 v[76:77], v[70:71], v[82:83] op_sel_hi:[0,1]
	v_mul_f32_e32 v53, v79, v47
	v_pk_fma_f32 v[38:39], v[38:39], v[58:59], v[74:75] op_sel_hi:[1,0,1]
	v_pk_fma_f32 v[36:37], v[36:37], v[58:59], v[76:77] op_sel_hi:[1,0,1]
	ds_read_b128 v[74:77], v67 offset:12336
	s_waitcnt lgkmcnt(1)
	v_mul_f32_e32 v55, v55, v43
	v_fmac_f32_e32 v53, v78, v46
	v_fmac_f32_e32 v55, v54, v42
	v_mul_f32_e32 v54, v57, v41
	v_add_f32_e32 v53, v53, v59
	v_fmac_f32_e32 v54, v56, v40
	v_add_f32_e32 v53, 0, v53
	v_add_f32_e32 v54, v55, v54
	v_add_f32_e32 v53, v54, v53
	ds_read_b128 v[54:57], v67 offset:12320
	s_waitcnt lgkmcnt(0)
	v_mul_f32_e32 v55, v55, v37
	v_fmac_f32_e32 v55, v54, v36
	v_mul_f32_e32 v54, v57, v39
	v_fmac_f32_e32 v54, v56, v38
	v_add_f32_e32 v54, v55, v54
	v_add_f32_e32 v53, v54, v53
	v_pk_mul_f32 v[54:55], v[70:71], v[88:89] op_sel_hi:[0,1]
	v_pk_mul_f32 v[56:57], v[70:71], v[86:87] op_sel_hi:[0,1]
	v_pk_fma_f32 v[34:35], v[34:35], v[58:59], v[54:55] op_sel_hi:[1,0,1]
	v_pk_fma_f32 v[32:33], v[32:33], v[58:59], v[56:57] op_sel_hi:[1,0,1]
	v_mul_f32_e32 v55, v77, v35
	v_mul_f32_e32 v54, v75, v33
	v_fmac_f32_e32 v54, v74, v32
	v_fmac_f32_e32 v55, v76, v34
	v_add_f32_e32 v54, v54, v55
	v_add_f32_e32 v53, v53, v54
	ds_bpermute_b32 v54, v61, v53
	s_waitcnt lgkmcnt(0)
	v_add_f32_e32 v53, v53, v54
	ds_bpermute_b32 v54, v62, v53
	s_waitcnt lgkmcnt(0)
	v_add_f32_e32 v53, v53, v54
	ds_bpermute_b32 v54, v63, v53
	s_and_saveexec_b64 s[14:15], s[6:7]
	s_cbranch_execz .Lssd0_691
	ds_read_b32 v55, v64 offset:44288
	s_waitcnt lgkmcnt(1)
	v_add_f32_e32 v53, v53, v54
	v_fmac_f32_e32 v53, v66, v52
	s_waitcnt lgkmcnt(0)
	v_mul_f32_e32 v56, 0xbfb8aa3b, v55
	v_exp_f32_e32 v56, v56
	s_nop 0
	v_add_f32_e32 v54, 1.0, v56
	v_div_scale_f32 v56, s[2:3], v54, v54, v55
	v_rcp_f32_e32 v57, v56
	v_div_scale_f32 v52, vcc, v55, v54, v55
	v_fma_f32 v58, -v56, v57, 1.0
	v_fmac_f32_e32 v57, v58, v57
	v_mul_f32_e32 v58, v52, v57
	v_fma_f32 v59, -v56, v58, v52
	v_fmac_f32_e32 v58, v59, v57
	v_fma_f32 v52, -v56, v58, v52
	v_div_fmas_f32 v52, v52, v57, v58
	v_div_fixup_f32 v52, v52, v54, v55
	v_mul_f32_e32 v52, v53, v52
	ds_write_b32 v64, v52 offset:32000
.Lssd0_691:
	s_or_b64 exec, exec, s[14:15]
	v_mov_b32_e32 v52, s1
	ds_read_b32 v56, v52 offset:96
	ds_read_b32 v69, v64 offset:14336
	s_waitcnt lgkmcnt(1)
	v_mul_f32_e32 v52, v56, v68
	v_mul_f32_e32 v52, 0xbfb8aa3b, v52
	v_exp_f32_e32 v70, v52
	ds_read_b128 v[52:55], v67 offset:17408
	ds_read_b128 v[74:77], v67 offset:17424
	ds_read_b128 v[78:81], v67 offset:19456
	s_waitcnt lgkmcnt(3)
	v_mul_f32_e32 v72, v56, v69
	v_pk_mul_f32 v[56:57], v[44:45], v[70:71] op_sel_hi:[1,0]
	v_pk_mul_f32 v[58:59], v[46:47], v[70:71] op_sel_hi:[1,0]
	s_waitcnt lgkmcnt(2)
	v_pk_fma_f32 v[56:57], v[54:55], v[72:73], v[56:57] op_sel_hi:[1,0,1]
	v_pk_fma_f32 v[58:59], v[52:53], v[72:73], v[58:59] op_sel_hi:[1,0,1]
	s_waitcnt lgkmcnt(0)
	v_mul_f32_e32 v53, v81, v57
	v_mul_f32_e32 v52, v79, v59
	ds_read_b128 v[44:47], v67 offset:17440
	ds_read_b128 v[82:85], v67 offset:17456
	ds_read_b128 v[86:89], v67 offset:19472
	v_fmac_f32_e32 v52, v78, v58
	v_fmac_f32_e32 v53, v80, v56
	v_add_f32_e32 v52, v52, v53
	v_add_f32_e32 v71, 0, v52
	v_pk_mul_f32 v[40:41], v[40:41], v[70:71] op_sel_hi:[1,0]
	v_pk_mul_f32 v[52:53], v[42:43], v[70:71] op_sel_hi:[1,0]
	v_pk_fma_f32 v[42:43], v[72:73], v[76:77], v[40:41] op_sel_hi:[0,1,1]
	v_pk_fma_f32 v[54:55], v[72:73], v[74:75], v[52:53] op_sel_hi:[0,1,1]
	ds_read_b128 v[74:77], v67 offset:19488
	s_waitcnt lgkmcnt(1)
	v_mul_f32_e32 v40, v87, v55
	v_mul_f32_e32 v41, v89, v43
	v_fmac_f32_e32 v40, v86, v54
	v_fmac_f32_e32 v41, v88, v42
	v_add_f32_e32 v40, v40, v41
	v_add_f32_e32 v52, v40, v71
	v_pk_mul_f32 v[40:41], v[72:73], v[46:47] op_sel_hi:[0,1]
	v_pk_mul_f32 v[44:45], v[72:73], v[44:45] op_sel_hi:[0,1]
	v_pk_fma_f32 v[40:41], v[38:39], v[70:71], v[40:41] op_sel_hi:[1,0,1]
	v_pk_fma_f32 v[46:47], v[36:37], v[70:71], v[44:45] op_sel_hi:[1,0,1]
	ds_read_b128 v[36:39], v67 offset:19504
	s_waitcnt lgkmcnt(1)
	v_mul_f32_e32 v44, v75, v47
	v_mul_f32_e32 v45, v77, v41
	v_fmac_f32_e32 v44, v74, v46
	v_fmac_f32_e32 v45, v76, v40
	v_add_f32_e32 v44, v44, v45
	v_add_f32_e32 v71, v44, v52
	v_pk_mul_f32 v[44:45], v[72:73], v[84:85] op_sel_hi:[0,1]
	v_pk_mul_f32 v[52:53], v[72:73], v[82:83] op_sel_hi:[0,1]
	v_pk_fma_f32 v[44:45], v[34:35], v[70:71], v[44:45] op_sel_hi:[1,0,1]
	v_pk_fma_f32 v[52:53], v[32:33], v[70:71], v[52:53] op_sel_hi:[1,0,1]
	s_waitcnt lgkmcnt(0)
	v_mul_f32_e32 v33, v39, v45
	v_mul_f32_e32 v32, v37, v53
	v_fmac_f32_e32 v32, v36, v52
	v_fmac_f32_e32 v33, v38, v44
	v_add_f32_e32 v32, v32, v33
	v_add_f32_e32 v32, v71, v32
	ds_bpermute_b32 v33, v61, v32
	s_waitcnt lgkmcnt(0)
	v_add_f32_e32 v32, v32, v33
	ds_bpermute_b32 v33, v62, v32
	s_waitcnt lgkmcnt(0)
	v_add_f32_e32 v32, v32, v33
	ds_bpermute_b32 v33, v63, v32
	s_and_saveexec_b64 s[14:15], s[6:7]
	s_cbranch_execz .Lssd0_693
	ds_read_b32 v34, v64 offset:47360
	s_waitcnt lgkmcnt(1)
	v_add_f32_e32 v32, v32, v33
	v_fmac_f32_e32 v32, v66, v69
	s_waitcnt lgkmcnt(0)
	v_mul_f32_e32 v35, 0xbfb8aa3b, v34
	v_exp_f32_e32 v35, v35
	s_nop 0
	v_add_f32_e32 v33, 1.0, v35
	v_div_scale_f32 v35, s[2:3], v33, v33, v34
	v_rcp_f32_e32 v36, v35
	v_div_scale_f32 v37, vcc, v34, v33, v34
	v_fma_f32 v38, -v35, v36, 1.0
	v_fmac_f32_e32 v36, v38, v36
	v_mul_f32_e32 v38, v37, v36
	v_fma_f32 v39, -v35, v38, v37
	v_fmac_f32_e32 v38, v39, v36
	v_fma_f32 v35, -v35, v38, v37
	v_div_fmas_f32 v35, v35, v36, v38
	v_div_fixup_f32 v33, v35, v33, v34
	v_mul_f32_e32 v32, v32, v33
	ds_write_b32 v64, v32 offset:35072
.Lssd0_693:
	s_or_b64 exec, exec, s[14:15]
	v_mov_b32_e32 v32, s1
	ds_read_b32 v70, v32 offset:144
	ds_read_b32 v69, v64 offset:21504
	s_waitcnt lgkmcnt(1)
	v_mul_f32_e32 v32, v70, v68
	v_mul_f32_e32 v32, 0xbfb8aa3b, v32
	v_exp_f32_e32 v68, v32
	ds_read_b128 v[32:35], v67 offset:24576
	ds_read_b128 v[36:39], v67 offset:24592
	ds_read_b128 v[74:77], v67 offset:26624
	s_waitcnt lgkmcnt(3)
	v_mul_f32_e32 v70, v70, v69
	v_pk_mul_f32 v[82:83], v[56:57], v[68:69] op_sel_hi:[1,0]
	v_pk_mul_f32 v[84:85], v[58:59], v[68:69] op_sel_hi:[1,0]
	s_waitcnt lgkmcnt(2)
	v_pk_fma_f32 v[34:35], v[34:35], v[70:71], v[82:83] op_sel_hi:[1,0,1]
	v_pk_fma_f32 v[32:33], v[32:33], v[70:71], v[84:85] op_sel_hi:[1,0,1]
	ds_read_b128 v[56:59], v67 offset:24608
	ds_read_b128 v[78:81], v67 offset:24624
	ds_read_b128 v[82:85], v67 offset:26640
	s_waitcnt lgkmcnt(3)
	v_mul_f32_e32 v71, v75, v33
	v_mul_f32_e32 v72, v77, v35
	v_fmac_f32_e32 v71, v74, v32
	v_fmac_f32_e32 v72, v76, v34
	v_add_f32_e32 v71, v71, v72
	v_add_f32_e32 v71, 0, v71
	v_pk_mul_f32 v[42:43], v[42:43], v[68:69] op_sel_hi:[1,0]
	v_pk_mul_f32 v[54:55], v[54:55], v[68:69] op_sel_hi:[1,0]
	v_pk_fma_f32 v[38:39], v[70:71], v[38:39], v[42:43] op_sel_hi:[0,1,1]
	v_pk_fma_f32 v[36:37], v[70:71], v[36:37], v[54:55] op_sel_hi:[0,1,1]
	ds_read_b128 v[74:77], v67 offset:26656
	s_waitcnt lgkmcnt(1)
	v_mul_f32_e32 v42, v83, v37
	v_mul_f32_e32 v43, v85, v39
	v_fmac_f32_e32 v42, v82, v36
	v_fmac_f32_e32 v43, v84, v38
	v_add_f32_e32 v42, v42, v43
	v_add_f32_e32 v71, v42, v71
	v_pk_mul_f32 v[42:43], v[70:71], v[58:59] op_sel_hi:[0,1]
	v_pk_mul_f32 v[54:55], v[70:71], v[56:57] op_sel_hi:[0,1]
	v_pk_fma_f32 v[42:43], v[40:41], v[68:69], v[42:43] op_sel_hi:[1,0,1]
	v_pk_fma_f32 v[40:41], v[46:47], v[68:69], v[54:55] op_sel_hi:[1,0,1]
	ds_read_b128 v[54:57], v67 offset:26672
	s_waitcnt lgkmcnt(1)
	v_mul_f32_e32 v46, v75, v41
	v_mul_f32_e32 v47, v77, v43
	v_fmac_f32_e32 v46, v74, v40
	v_fmac_f32_e32 v47, v76, v42
	v_add_f32_e32 v46, v46, v47
	v_add_f32_e32 v67, v46, v71
	v_pk_mul_f32 v[46:47], v[70:71], v[80:81] op_sel_hi:[0,1]
	v_pk_mul_f32 v[58:59], v[70:71], v[78:79] op_sel_hi:[0,1]
	v_pk_fma_f32 v[46:47], v[44:45], v[68:69], v[46:47] op_sel_hi:[1,0,1]
	v_pk_fma_f32 v[44:45], v[52:53], v[68:69], v[58:59] op_sel_hi:[1,0,1]
	s_waitcnt lgkmcnt(0)
	v_mul_f32_e32 v53, v57, v47
	v_mul_f32_e32 v52, v55, v45
	v_fmac_f32_e32 v52, v54, v44
	v_fmac_f32_e32 v53, v56, v46
	v_add_f32_e32 v52, v52, v53
	v_add_f32_e32 v52, v67, v52
	ds_bpermute_b32 v53, v61, v52
	s_waitcnt lgkmcnt(0)
	v_add_f32_e32 v52, v52, v53
	ds_bpermute_b32 v53, v62, v52
	s_waitcnt lgkmcnt(0)
	v_add_f32_e32 v52, v52, v53
	ds_bpermute_b32 v53, v63, v52
	s_and_saveexec_b64 s[14:15], s[6:7]
	s_cbranch_execz .Lssd0_tail
	ds_read_b32 v54, v64 offset:50432
	s_waitcnt lgkmcnt(1)
	v_add_f32_e32 v52, v52, v53
	v_fmac_f32_e32 v52, v66, v69
	s_waitcnt lgkmcnt(0)
	v_mul_f32_e32 v55, 0xbfb8aa3b, v54
	v_exp_f32_e32 v55, v55
	s_nop 0
	v_add_f32_e32 v53, 1.0, v55
	v_div_scale_f32 v55, s[2:3], v53, v53, v54
	v_rcp_f32_e32 v56, v55
	v_div_scale_f32 v57, vcc, v54, v53, v54
	v_fma_f32 v58, -v55, v56, 1.0
	v_fmac_f32_e32 v56, v58, v56
	v_mul_f32_e32 v58, v57, v56
	v_fma_f32 v59, -v55, v58, v57
	v_fmac_f32_e32 v58, v59, v56
	v_fma_f32 v55, -v55, v58, v57
	v_div_fmas_f32 v55, v55, v56, v58
	v_div_fixup_f32 v53, v55, v53, v54
	v_mul_f32_e32 v52, v52, v53
	ds_write_b32 v64, v52 offset:38144
	s_branch .Lssd0_tail
.Lssd0_tail:
	s_or_b64 exec, exec, s[14:15]
	s_add_i32 s0, s0, 1
	s_add_i32 s1, s1, 4
	s_waitcnt lgkmcnt(0)
	v_lshl_add_u64 v[52:53], v[50:51], 0, s[8:9]
	s_add_u32 s8, s8, 0x8000
	s_addc_u32 s9, s9, 0
	v_add_co_u32_e32 v52, vcc, 0x2fb35000, v52
	s_add_u32 s12, s12, 4
	s_nop 0
	v_addc_co_u32_e32 v53, vcc, 0, v53, vcc
	s_addc_u32 s13, s13, 0
	global_store_dwordx4 v[52:53], v[32:35], off nt
	global_store_dwordx4 v[52:53], v[36:39], off offset:16 nt
	global_store_dwordx4 v[52:53], v[40:43], off offset:32 nt
	global_store_dwordx4 v[52:53], v[44:47], off offset:48 nt
	s_add_u32 s10, s10, 4
	s_addc_u32 s11, s11, 0
	v_add_u32_e32 v64, 0x100, v64
	s_cmp_eq_u32 s8, 0x60000
	s_cbranch_scc1 .LBB0_695
.Lssd_body1:
	s_cmp_gt_u32 s0, 9
	s_cbranch_scc1 .Lssd1_nopf
	v_lshl_add_u64 v[90:91], v[48:49], 0, s[8:9]
	s_mov_b64 s[2:3], 0x10000
	v_lshl_add_u64 v[90:91], v[90:91], 0, s[2:3]
	global_load_dwordx4 v[32:35], v[90:91], off offset:48 nt
	global_load_dwordx4 v[36:39], v[90:91], off offset:32 nt
	global_load_dwordx4 v[40:43], v[90:91], off offset:16 nt
	global_load_dwordx4 v[44:47], v[90:91], off nt

.Lssd1_wd:
	s_waitcnt lgkmcnt(0)
	v_mov_b32_e32 v52, s16
	v_mov_b32_e32 v66, s17
	v_mul_f32_e32 v52, 0x3fb8aa3b, v52
	v_exp_f32_e32 v68, v52
	v_mov_b32_e32 v52, s1
	ds_read_b32 v53, v52
	s_waitcnt lgkmcnt(0)
	v_mul_f32_e64 v52, v53, -v68
	v_mul_f32_e32 v52, 0x3fb8aa3b, v52
	v_exp_f32_e32 v58, v52
	ds_read_b32 v52, v64
	ds_read_b128 v[54:57], v67 offset:3072
	ds_read_b128 v[74:77], v67 offset:3088
	ds_read_b128 v[78:81], v67 offset:3104
	ds_read_b128 v[82:85], v67 offset:3120
	v_pk_mul_f32 v[2:3], v[2:3], v[58:59] op_sel_hi:[1,0]
	v_pk_mul_f32 v[86:87], v[0:1], v[58:59] op_sel_hi:[1,0]
	s_waitcnt lgkmcnt(4)
	v_mul_f32_e32 v70, v53, v52
	s_waitcnt lgkmcnt(3)
	v_pk_fma_f32 v[0:1], v[56:57], v[70:71], v[2:3] op_sel_hi:[1,0,1]
	v_pk_fma_f32 v[2:3], v[54:55], v[70:71], v[86:87] op_sel_hi:[1,0,1]
	ds_read_b128 v[54:57], v67 offset:5120
	v_pk_mul_f32 v[14:15], v[14:15], v[58:59] op_sel_hi:[1,0]
	s_waitcnt lgkmcnt(0)
	v_mul_f32_e32 v53, v55, v3
	v_fmac_f32_e32 v53, v54, v2
	v_mul_f32_e32 v54, v57, v1
	v_fmac_f32_e32 v54, v56, v0
	v_add_f32_e32 v53, v53, v54
	v_pk_mul_f32 v[54:55], v[12:13], v[58:59] op_sel_hi:[1,0]
	v_pk_fma_f32 v[12:13], v[70:71], v[76:77], v[14:15] op_sel_hi:[0,1,1]
	v_pk_fma_f32 v[14:15], v[70:71], v[74:75], v[54:55] op_sel_hi:[0,1,1]
	ds_read_b128 v[54:57], v67 offset:5136
	v_add_f32_e32 v53, 0, v53
	s_waitcnt lgkmcnt(0)
	v_mul_f32_e32 v55, v55, v15
	v_fmac_f32_e32 v55, v54, v14
	v_mul_f32_e32 v54, v57, v13
	v_fmac_f32_e32 v54, v56, v12
	v_add_f32_e32 v54, v55, v54
	v_add_f32_e32 v53, v54, v53
	v_pk_mul_f32 v[54:55], v[70:71], v[78:79] op_sel_hi:[0,1]
	v_pk_mul_f32 v[56:57], v[70:71], v[80:81] op_sel_hi:[0,1]
	v_pk_fma_f32 v[10:11], v[10:11], v[58:59], v[56:57] op_sel_hi:[1,0,1]
	v_pk_fma_f32 v[8:9], v[8:9], v[58:59], v[54:55] op_sel_hi:[1,0,1]
	ds_read_b128 v[54:57], v67 offset:5152
	s_waitcnt lgkmcnt(0)
	v_mul_f32_e32 v55, v55, v9
	v_fmac_f32_e32 v55, v54, v8
	v_mul_f32_e32 v54, v57, v11
	v_fmac_f32_e32 v54, v56, v10
	v_add_f32_e32 v54, v55, v54
	v_add_f32_e32 v53, v54, v53
	v_pk_mul_f32 v[54:55], v[70:71], v[82:83] op_sel_hi:[0,1]
	v_pk_mul_f32 v[56:57], v[70:71], v[84:85] op_sel_hi:[0,1]
	v_pk_fma_f32 v[6:7], v[6:7], v[58:59], v[56:57] op_sel_hi:[1,0,1]
	v_pk_fma_f32 v[4:5], v[4:5], v[58:59], v[54:55] op_sel_hi:[1,0,1]
	ds_read_b128 v[54:57], v67 offset:5168
	s_waitcnt lgkmcnt(0)
	v_mul_f32_e32 v55, v55, v5
	v_fmac_f32_e32 v55, v54, v4
	v_mul_f32_e32 v54, v57, v7
	v_fmac_f32_e32 v54, v56, v6
	v_add_f32_e32 v54, v55, v54
	v_add_f32_e32 v53, v53, v54
	ds_bpermute_b32 v54, v61, v53
	s_waitcnt lgkmcnt(0)
	v_add_f32_e32 v53, v53, v54
	ds_bpermute_b32 v54, v62, v53
	s_waitcnt lgkmcnt(0)
	v_add_f32_e32 v53, v53, v54
	ds_bpermute_b32 v54, v63, v53
	s_and_saveexec_b64 s[14:15], s[6:7]
	s_cbranch_execz .Lssd1_689
	ds_read_b32 v55, v64 offset:41216
	s_waitcnt lgkmcnt(1)
	v_add_f32_e32 v53, v53, v54
	v_fmac_f32_e32 v53, v66, v52
	s_waitcnt lgkmcnt(0)
	v_mul_f32_e32 v56, 0xbfb8aa3b, v55
	v_exp_f32_e32 v56, v56
	s_nop 0
	v_add_f32_e32 v54, 1.0, v56
	v_div_scale_f32 v56, s[2:3], v54, v54, v55
	v_rcp_f32_e32 v57, v56
	v_div_scale_f32 v52, vcc, v55, v54, v55
	v_fma_f32 v58, -v56, v57, 1.0
	v_fmac_f32_e32 v57, v58, v57
	v_mul_f32_e32 v58, v52, v57
	v_fma_f32 v59, -v56, v58, v52
	v_fmac_f32_e32 v58, v59, v57
	v_fma_f32 v52, -v56, v58, v52
	v_div_fmas_f32 v52, v52, v57, v58
	v_div_fixup_f32 v52, v52, v54, v55
	v_mul_f32_e32 v52, v53, v52
	ds_write_b32 v64, v52 offset:28928
.Lssd1_689:
	s_or_b64 exec, exec, s[14:15]
	v_mov_b32_e32 v52, s1
	ds_read_b32 v53, v52 offset:48
	ds_read_b32 v52, v64 offset:7168
	s_waitcnt lgkmcnt(1)
	v_mul_f32_e32 v54, v53, v68
	v_mul_f32_e32 v54, 0xbfb8aa3b, v54
	v_exp_f32_e32 v58, v54
	ds_read_b128 v[54:57], v67 offset:10240
	ds_read_b128 v[74:77], v67 offset:10256
	ds_read_b128 v[78:81], v67 offset:12288
	s_waitcnt lgkmcnt(3)
	v_mul_f32_e32 v70, v53, v52
	ds_read_b128 v[82:85], v67 offset:10272
	ds_read_b128 v[86:89], v67 offset:10288
	v_pk_mul_f32 v[0:1], v[0:1], v[58:59] op_sel_hi:[1,0]
	v_pk_mul_f32 v[2:3], v[2:3], v[58:59] op_sel_hi:[1,0]
	s_waitcnt lgkmcnt(4)
	v_pk_fma_f32 v[0:1], v[56:57], v[70:71], v[0:1] op_sel_hi:[1,0,1]
	v_pk_fma_f32 v[2:3], v[54:55], v[70:71], v[2:3] op_sel_hi:[1,0,1]
	ds_read_b128 v[54:57], v67 offset:12304
	s_waitcnt lgkmcnt(3)
	v_mul_f32_e32 v59, v81, v1
	v_fmac_f32_e32 v59, v80, v0
	v_pk_mul_f32 v[12:13], v[12:13], v[58:59] op_sel_hi:[1,0]
	v_pk_mul_f32 v[14:15], v[14:15], v[58:59] op_sel_hi:[1,0]
	v_pk_fma_f32 v[12:13], v[70:71], v[76:77], v[12:13] op_sel_hi:[0,1,1]
	v_pk_fma_f32 v[14:15], v[70:71], v[74:75], v[14:15] op_sel_hi:[0,1,1]
	s_waitcnt lgkmcnt(2)
	v_pk_mul_f32 v[74:75], v[70:71], v[84:85] op_sel_hi:[0,1]
	v_pk_mul_f32 v[76:77], v[70:71], v[82:83] op_sel_hi:[0,1]
	v_mul_f32_e32 v53, v79, v3
	v_pk_fma_f32 v[10:11], v[10:11], v[58:59], v[74:75] op_sel_hi:[1,0,1]
	v_pk_fma_f32 v[8:9], v[8:9], v[58:59], v[76:77] op_sel_hi:[1,0,1]
	ds_read_b128 v[74:77], v67 offset:12336
	s_waitcnt lgkmcnt(1)
	v_mul_f32_e32 v55, v55, v15
	v_fmac_f32_e32 v53, v78, v2
	v_fmac_f32_e32 v55, v54, v14
	v_mul_f32_e32 v54, v57, v13
	v_add_f32_e32 v53, v53, v59
	v_fmac_f32_e32 v54, v56, v12
	v_add_f32_e32 v53, 0, v53
	v_add_f32_e32 v54, v55, v54
	v_add_f32_e32 v53, v54, v53
	ds_read_b128 v[54:57], v67 offset:12320
	s_waitcnt lgkmcnt(0)
	v_mul_f32_e32 v55, v55, v9
	v_fmac_f32_e32 v55, v54, v8
	v_mul_f32_e32 v54, v57, v11
	v_fmac_f32_e32 v54, v56, v10
	v_add_f32_e32 v54, v55, v54
	v_add_f32_e32 v53, v54, v53
	v_pk_mul_f32 v[54:55], v[70:71], v[88:89] op_sel_hi:[0,1]
	v_pk_mul_f32 v[56:57], v[70:71], v[86:87] op_sel_hi:[0,1]
	v_pk_fma_f32 v[6:7], v[6:7], v[58:59], v[54:55] op_sel_hi:[1,0,1]
	v_pk_fma_f32 v[4:5], v[4:5], v[58:59], v[56:57] op_sel_hi:[1,0,1]
	v_mul_f32_e32 v55, v77, v7
	v_mul_f32_e32 v54, v75, v5
	v_fmac_f32_e32 v54, v74, v4
	v_fmac_f32_e32 v55, v76, v6
	v_add_f32_e32 v54, v54, v55
	v_add_f32_e32 v53, v53, v54
	ds_bpermute_b32 v54, v61, v53
	s_waitcnt lgkmcnt(0)
	v_add_f32_e32 v53, v53, v54
	ds_bpermute_b32 v54, v62, v53
	s_waitcnt lgkmcnt(0)
	v_add_f32_e32 v53, v53, v54
	ds_bpermute_b32 v54, v63, v53
	s_and_saveexec_b64 s[14:15], s[6:7]
	s_cbranch_execz .Lssd1_691
	ds_read_b32 v55, v64 offset:44288
	s_waitcnt lgkmcnt(1)
	v_add_f32_e32 v53, v53, v54
	v_fmac_f32_e32 v53, v66, v52
	s_waitcnt lgkmcnt(0)
	v_mul_f32_e32 v56, 0xbfb8aa3b, v55
	v_exp_f32_e32 v56, v56
	s_nop 0
	v_add_f32_e32 v54, 1.0, v56
	v_div_scale_f32 v56, s[2:3], v54, v54, v55
	v_rcp_f32_e32 v57, v56
	v_div_scale_f32 v52, vcc, v55, v54, v55
	v_fma_f32 v58, -v56, v57, 1.0
	v_fmac_f32_e32 v57, v58, v57
	v_mul_f32_e32 v58, v52, v57
	v_fma_f32 v59, -v56, v58, v52
	v_fmac_f32_e32 v58, v59, v57
	v_fma_f32 v52, -v56, v58, v52
	v_div_fmas_f32 v52, v52, v57, v58
	v_div_fixup_f32 v52, v52, v54, v55
	v_mul_f32_e32 v52, v53, v52
	ds_write_b32 v64, v52 offset:32000
.Lssd1_691:
	s_or_b64 exec, exec, s[14:15]
	v_mov_b32_e32 v52, s1
	ds_read_b32 v56, v52 offset:96
	ds_read_b32 v69, v64 offset:14336
	s_waitcnt lgkmcnt(1)
	v_mul_f32_e32 v52, v56, v68
	v_mul_f32_e32 v52, 0xbfb8aa3b, v52
	v_exp_f32_e32 v70, v52
	ds_read_b128 v[52:55], v67 offset:17408
	ds_read_b128 v[74:77], v67 offset:17424
	ds_read_b128 v[78:81], v67 offset:19456
	s_waitcnt lgkmcnt(3)
	v_mul_f32_e32 v72, v56, v69
	v_pk_mul_f32 v[56:57], v[0:1], v[70:71] op_sel_hi:[1,0]
	v_pk_mul_f32 v[58:59], v[2:3], v[70:71] op_sel_hi:[1,0]
	s_waitcnt lgkmcnt(2)
	v_pk_fma_f32 v[56:57], v[54:55], v[72:73], v[56:57] op_sel_hi:[1,0,1]
	v_pk_fma_f32 v[58:59], v[52:53], v[72:73], v[58:59] op_sel_hi:[1,0,1]
	s_waitcnt lgkmcnt(0)
	v_mul_f32_e32 v53, v81, v57
	v_mul_f32_e32 v52, v79, v59
	ds_read_b128 v[0:3], v67 offset:17440
	ds_read_b128 v[82:85], v67 offset:17456
	ds_read_b128 v[86:89], v67 offset:19472
	v_fmac_f32_e32 v52, v78, v58
	v_fmac_f32_e32 v53, v80, v56
	v_add_f32_e32 v52, v52, v53
	v_add_f32_e32 v71, 0, v52
	v_pk_mul_f32 v[12:13], v[12:13], v[70:71] op_sel_hi:[1,0]
	v_pk_mul_f32 v[52:53], v[14:15], v[70:71] op_sel_hi:[1,0]
	v_pk_fma_f32 v[14:15], v[72:73], v[76:77], v[12:13] op_sel_hi:[0,1,1]
	v_pk_fma_f32 v[54:55], v[72:73], v[74:75], v[52:53] op_sel_hi:[0,1,1]
	ds_read_b128 v[74:77], v67 offset:19488
	s_waitcnt lgkmcnt(1)
	v_mul_f32_e32 v12, v87, v55
	v_mul_f32_e32 v13, v89, v15
	v_fmac_f32_e32 v12, v86, v54
	v_fmac_f32_e32 v13, v88, v14
	v_add_f32_e32 v12, v12, v13
	v_add_f32_e32 v52, v12, v71
	v_pk_mul_f32 v[12:13], v[72:73], v[2:3] op_sel_hi:[0,1]
	v_pk_mul_f32 v[0:1], v[72:73], v[0:1] op_sel_hi:[0,1]
	v_pk_fma_f32 v[12:13], v[10:11], v[70:71], v[12:13] op_sel_hi:[1,0,1]
	v_pk_fma_f32 v[2:3], v[8:9], v[70:71], v[0:1] op_sel_hi:[1,0,1]
	ds_read_b128 v[8:11], v67 offset:19504
	s_waitcnt lgkmcnt(1)
	v_mul_f32_e32 v0, v75, v3
	v_mul_f32_e32 v1, v77, v13
	v_fmac_f32_e32 v0, v74, v2
	v_fmac_f32_e32 v1, v76, v12
	v_add_f32_e32 v0, v0, v1
	v_add_f32_e32 v71, v0, v52
	v_pk_mul_f32 v[0:1], v[72:73], v[84:85] op_sel_hi:[0,1]
	v_pk_mul_f32 v[52:53], v[72:73], v[82:83] op_sel_hi:[0,1]
	v_pk_fma_f32 v[0:1], v[6:7], v[70:71], v[0:1] op_sel_hi:[1,0,1]
	v_pk_fma_f32 v[52:53], v[4:5], v[70:71], v[52:53] op_sel_hi:[1,0,1]
	s_waitcnt lgkmcnt(0)
	v_mul_f32_e32 v5, v11, v1
	v_mul_f32_e32 v4, v9, v53
	v_fmac_f32_e32 v4, v8, v52
	v_fmac_f32_e32 v5, v10, v0
	v_add_f32_e32 v4, v4, v5
	v_add_f32_e32 v4, v71, v4
	ds_bpermute_b32 v5, v61, v4
	s_waitcnt lgkmcnt(0)
	v_add_f32_e32 v4, v4, v5
	ds_bpermute_b32 v5, v62, v4
	s_waitcnt lgkmcnt(0)
	v_add_f32_e32 v4, v4, v5
	ds_bpermute_b32 v5, v63, v4
	s_and_saveexec_b64 s[14:15], s[6:7]
	s_cbranch_execz .Lssd1_693
	ds_read_b32 v6, v64 offset:47360
	s_waitcnt lgkmcnt(1)
	v_add_f32_e32 v4, v4, v5
	v_fmac_f32_e32 v4, v66, v69
	s_waitcnt lgkmcnt(0)
	v_mul_f32_e32 v7, 0xbfb8aa3b, v6
	v_exp_f32_e32 v7, v7
	s_nop 0
	v_add_f32_e32 v5, 1.0, v7
	v_div_scale_f32 v7, s[2:3], v5, v5, v6
	v_rcp_f32_e32 v8, v7
	v_div_scale_f32 v9, vcc, v6, v5, v6
	v_fma_f32 v10, -v7, v8, 1.0
	v_fmac_f32_e32 v8, v10, v8
	v_mul_f32_e32 v10, v9, v8
	v_fma_f32 v11, -v7, v10, v9
	v_fmac_f32_e32 v10, v11, v8
	v_fma_f32 v7, -v7, v10, v9
	v_div_fmas_f32 v7, v7, v8, v10
	v_div_fixup_f32 v5, v7, v5, v6
	v_mul_f32_e32 v4, v4, v5
	ds_write_b32 v64, v4 offset:35072
.Lssd1_693:
	s_or_b64 exec, exec, s[14:15]
	v_mov_b32_e32 v4, s1
	ds_read_b32 v70, v4 offset:144
	ds_read_b32 v69, v64 offset:21504
	s_waitcnt lgkmcnt(1)
	v_mul_f32_e32 v4, v70, v68
	v_mul_f32_e32 v4, 0xbfb8aa3b, v4
	v_exp_f32_e32 v68, v4
	ds_read_b128 v[4:7], v67 offset:24576
	ds_read_b128 v[8:11], v67 offset:24592
	ds_read_b128 v[74:77], v67 offset:26624
	s_waitcnt lgkmcnt(3)
	v_mul_f32_e32 v70, v70, v69
	v_pk_mul_f32 v[82:83], v[56:57], v[68:69] op_sel_hi:[1,0]
	v_pk_mul_f32 v[84:85], v[58:59], v[68:69] op_sel_hi:[1,0]
	s_waitcnt lgkmcnt(2)
	v_pk_fma_f32 v[6:7], v[6:7], v[70:71], v[82:83] op_sel_hi:[1,0,1]
	v_pk_fma_f32 v[4:5], v[4:5], v[70:71], v[84:85] op_sel_hi:[1,0,1]
	ds_read_b128 v[56:59], v67 offset:24608
	ds_read_b128 v[78:81], v67 offset:24624
	ds_read_b128 v[82:85], v67 offset:26640
	s_waitcnt lgkmcnt(3)
	v_mul_f32_e32 v71, v75, v5
	v_mul_f32_e32 v72, v77, v7
	v_fmac_f32_e32 v71, v74, v4
	v_fmac_f32_e32 v72, v76, v6
	v_add_f32_e32 v71, v71, v72
	v_add_f32_e32 v71, 0, v71
	v_pk_mul_f32 v[14:15], v[14:15], v[68:69] op_sel_hi:[1,0]
	v_pk_mul_f32 v[54:55], v[54:55], v[68:69] op_sel_hi:[1,0]
	v_pk_fma_f32 v[10:11], v[70:71], v[10:11], v[14:15] op_sel_hi:[0,1,1]
	v_pk_fma_f32 v[8:9], v[70:71], v[8:9], v[54:55] op_sel_hi:[0,1,1]
	ds_read_b128 v[74:77], v67 offset:26656
	s_waitcnt lgkmcnt(1)
	v_mul_f32_e32 v14, v83, v9
	v_mul_f32_e32 v15, v85, v11
	v_fmac_f32_e32 v14, v82, v8
	v_fmac_f32_e32 v15, v84, v10
	v_add_f32_e32 v14, v14, v15
	v_add_f32_e32 v71, v14, v71
	v_pk_mul_f32 v[14:15], v[70:71], v[58:59] op_sel_hi:[0,1]
	v_pk_mul_f32 v[54:55], v[70:71], v[56:57] op_sel_hi:[0,1]
	v_pk_fma_f32 v[14:15], v[12:13], v[68:69], v[14:15] op_sel_hi:[1,0,1]
	v_pk_fma_f32 v[12:13], v[2:3], v[68:69], v[54:55] op_sel_hi:[1,0,1]
	ds_read_b128 v[54:57], v67 offset:26672
	s_waitcnt lgkmcnt(1)
	v_mul_f32_e32 v2, v75, v13
	v_mul_f32_e32 v3, v77, v15
	v_fmac_f32_e32 v2, v74, v12
	v_fmac_f32_e32 v3, v76, v14
	v_add_f32_e32 v2, v2, v3
	v_add_f32_e32 v67, v2, v71
	v_pk_mul_f32 v[2:3], v[70:71], v[80:81] op_sel_hi:[0,1]
	v_pk_mul_f32 v[58:59], v[70:71], v[78:79] op_sel_hi:[0,1]
	v_pk_fma_f32 v[2:3], v[0:1], v[68:69], v[2:3] op_sel_hi:[1,0,1]
	v_pk_fma_f32 v[0:1], v[52:53], v[68:69], v[58:59] op_sel_hi:[1,0,1]
	s_waitcnt lgkmcnt(0)
	v_mul_f32_e32 v53, v57, v3
	v_mul_f32_e32 v52, v55, v1
	v_fmac_f32_e32 v52, v54, v0
	v_fmac_f32_e32 v53, v56, v2
	v_add_f32_e32 v52, v52, v53
	v_add_f32_e32 v52, v67, v52
	ds_bpermute_b32 v53, v61, v52
	s_waitcnt lgkmcnt(0)
	v_add_f32_e32 v52, v52, v53
	ds_bpermute_b32 v53, v62, v52
	s_waitcnt lgkmcnt(0)
	v_add_f32_e32 v52, v52, v53
	ds_bpermute_b32 v53, v63, v52
	s_and_saveexec_b64 s[14:15], s[6:7]
	s_cbranch_execz .Lssd1_tail
	ds_read_b32 v54, v64 offset:50432
	s_waitcnt lgkmcnt(1)
	v_add_f32_e32 v52, v52, v53
	v_fmac_f32_e32 v52, v66, v69
	s_waitcnt lgkmcnt(0)
	v_mul_f32_e32 v55, 0xbfb8aa3b, v54
	v_exp_f32_e32 v55, v55
	s_nop 0
	v_add_f32_e32 v53, 1.0, v55
	v_div_scale_f32 v55, s[2:3], v53, v53, v54
	v_rcp_f32_e32 v56, v55
	v_div_scale_f32 v57, vcc, v54, v53, v54
	v_fma_f32 v58, -v55, v56, 1.0
	v_fmac_f32_e32 v56, v58, v56
	v_mul_f32_e32 v58, v57, v56
	v_fma_f32 v59, -v55, v58, v57
	v_fmac_f32_e32 v58, v59, v56
	v_fma_f32 v55, -v55, v58, v57
	v_div_fmas_f32 v55, v55, v56, v58
	v_div_fixup_f32 v53, v55, v53, v54
	v_mul_f32_e32 v52, v52, v53
	ds_write_b32 v64, v52 offset:38144
	s_branch .Lssd1_tail
.Lssd1_tail:
	s_or_b64 exec, exec, s[14:15]
	s_add_i32 s0, s0, 1
	s_add_i32 s1, s1, 4
	s_waitcnt lgkmcnt(0)
	v_lshl_add_u64 v[52:53], v[50:51], 0, s[8:9]
	s_add_u32 s8, s8, 0x8000
	s_addc_u32 s9, s9, 0
	v_add_co_u32_e32 v52, vcc, 0x2fb35000, v52
	s_add_u32 s12, s12, 4
	s_nop 0
	v_addc_co_u32_e32 v53, vcc, 0, v53, vcc
	s_addc_u32 s13, s13, 0
	global_store_dwordx4 v[52:53], v[4:7], off nt
	global_store_dwordx4 v[52:53], v[8:11], off offset:16 nt
	global_store_dwordx4 v[52:53], v[12:15], off offset:32 nt
	global_store_dwordx4 v[52:53], v[0:3], off offset:48 nt
	s_add_u32 s10, s10, 4
	s_addc_u32 s11, s11, 0
	v_add_u32_e32 v64, 0x100, v64
	s_cmp_eq_u32 s8, 0x60000
	s_cbranch_scc1 .LBB0_695
.Lssd_body2:
	s_cmp_gt_u32 s0, 9
	s_cbranch_scc1 .Lssd2_nopf
	v_lshl_add_u64 v[90:91], v[48:49], 0, s[8:9]
	s_mov_b64 s[2:3], 0x10000
	v_lshl_add_u64 v[90:91], v[90:91], 0, s[2:3]
	global_load_dwordx4 v[4:7], v[90:91], off offset:48 nt
	global_load_dwordx4 v[8:11], v[90:91], off offset:32 nt
	global_load_dwordx4 v[12:15], v[90:91], off offset:16 nt
	global_load_dwordx4 v[0:3], v[90:91], off nt

.Lssd2_wd:
	s_waitcnt lgkmcnt(0)
	v_mov_b32_e32 v52, s16
	v_mov_b32_e32 v66, s17
	v_mul_f32_e32 v52, 0x3fb8aa3b, v52
	v_exp_f32_e32 v68, v52
	v_mov_b32_e32 v52, s1
	ds_read_b32 v53, v52
	s_waitcnt lgkmcnt(0)
	v_mul_f32_e64 v52, v53, -v68
	v_mul_f32_e32 v52, 0x3fb8aa3b, v52
	v_exp_f32_e32 v58, v52
	ds_read_b32 v52, v64
	ds_read_b128 v[54:57], v67 offset:3072
	ds_read_b128 v[74:77], v67 offset:3088
	ds_read_b128 v[78:81], v67 offset:3104
	ds_read_b128 v[82:85], v67 offset:3120
	v_pk_mul_f32 v[26:27], v[26:27], v[58:59] op_sel_hi:[1,0]
	v_pk_mul_f32 v[86:87], v[24:25], v[58:59] op_sel_hi:[1,0]
	s_waitcnt lgkmcnt(4)
	v_mul_f32_e32 v70, v53, v52
	s_waitcnt lgkmcnt(3)
	v_pk_fma_f32 v[24:25], v[56:57], v[70:71], v[26:27] op_sel_hi:[1,0,1]
	v_pk_fma_f32 v[26:27], v[54:55], v[70:71], v[86:87] op_sel_hi:[1,0,1]
	ds_read_b128 v[54:57], v67 offset:5120
	v_pk_mul_f32 v[30:31], v[30:31], v[58:59] op_sel_hi:[1,0]
	s_waitcnt lgkmcnt(0)
	v_mul_f32_e32 v53, v55, v27
	v_fmac_f32_e32 v53, v54, v26
	v_mul_f32_e32 v54, v57, v25
	v_fmac_f32_e32 v54, v56, v24
	v_add_f32_e32 v53, v53, v54
	v_pk_mul_f32 v[54:55], v[28:29], v[58:59] op_sel_hi:[1,0]
	v_pk_fma_f32 v[28:29], v[70:71], v[76:77], v[30:31] op_sel_hi:[0,1,1]
	v_pk_fma_f32 v[30:31], v[70:71], v[74:75], v[54:55] op_sel_hi:[0,1,1]
	ds_read_b128 v[54:57], v67 offset:5136
	v_add_f32_e32 v53, 0, v53
	s_waitcnt lgkmcnt(0)
	v_mul_f32_e32 v55, v55, v31
	v_fmac_f32_e32 v55, v54, v30
	v_mul_f32_e32 v54, v57, v29
	v_fmac_f32_e32 v54, v56, v28
	v_add_f32_e32 v54, v55, v54
	v_add_f32_e32 v53, v54, v53
	v_pk_mul_f32 v[54:55], v[70:71], v[78:79] op_sel_hi:[0,1]
	v_pk_mul_f32 v[56:57], v[70:71], v[80:81] op_sel_hi:[0,1]
	v_pk_fma_f32 v[22:23], v[22:23], v[58:59], v[56:57] op_sel_hi:[1,0,1]
	v_pk_fma_f32 v[20:21], v[20:21], v[58:59], v[54:55] op_sel_hi:[1,0,1]
	ds_read_b128 v[54:57], v67 offset:5152
	s_waitcnt lgkmcnt(0)
	v_mul_f32_e32 v55, v55, v21
	v_fmac_f32_e32 v55, v54, v20
	v_mul_f32_e32 v54, v57, v23
	v_fmac_f32_e32 v54, v56, v22
	v_add_f32_e32 v54, v55, v54
	v_add_f32_e32 v53, v54, v53
	v_pk_mul_f32 v[54:55], v[70:71], v[82:83] op_sel_hi:[0,1]
	v_pk_mul_f32 v[56:57], v[70:71], v[84:85] op_sel_hi:[0,1]
	v_pk_fma_f32 v[18:19], v[18:19], v[58:59], v[56:57] op_sel_hi:[1,0,1]
	v_pk_fma_f32 v[16:17], v[16:17], v[58:59], v[54:55] op_sel_hi:[1,0,1]
	ds_read_b128 v[54:57], v67 offset:5168
	s_waitcnt lgkmcnt(0)
	v_mul_f32_e32 v55, v55, v17
	v_fmac_f32_e32 v55, v54, v16
	v_mul_f32_e32 v54, v57, v19
	v_fmac_f32_e32 v54, v56, v18
	v_add_f32_e32 v54, v55, v54
	v_add_f32_e32 v53, v53, v54
	ds_bpermute_b32 v54, v61, v53
	s_waitcnt lgkmcnt(0)
	v_add_f32_e32 v53, v53, v54
	ds_bpermute_b32 v54, v62, v53
	s_waitcnt lgkmcnt(0)
	v_add_f32_e32 v53, v53, v54
	ds_bpermute_b32 v54, v63, v53
	s_and_saveexec_b64 s[14:15], s[6:7]
	s_cbranch_execz .Lssd2_689
	ds_read_b32 v55, v64 offset:41216
	s_waitcnt lgkmcnt(1)
	v_add_f32_e32 v53, v53, v54
	v_fmac_f32_e32 v53, v66, v52
	s_waitcnt lgkmcnt(0)
	v_mul_f32_e32 v56, 0xbfb8aa3b, v55
	v_exp_f32_e32 v56, v56
	s_nop 0
	v_add_f32_e32 v54, 1.0, v56
	v_div_scale_f32 v56, s[2:3], v54, v54, v55
	v_rcp_f32_e32 v57, v56
	v_div_scale_f32 v52, vcc, v55, v54, v55
	v_fma_f32 v58, -v56, v57, 1.0
	v_fmac_f32_e32 v57, v58, v57
	v_mul_f32_e32 v58, v52, v57
	v_fma_f32 v59, -v56, v58, v52
	v_fmac_f32_e32 v58, v59, v57
	v_fma_f32 v52, -v56, v58, v52
	v_div_fmas_f32 v52, v52, v57, v58
	v_div_fixup_f32 v52, v52, v54, v55
	v_mul_f32_e32 v52, v53, v52
	ds_write_b32 v64, v52 offset:28928
.Lssd2_689:
	s_or_b64 exec, exec, s[14:15]
	v_mov_b32_e32 v52, s1
	ds_read_b32 v53, v52 offset:48
	ds_read_b32 v52, v64 offset:7168
	s_waitcnt lgkmcnt(1)
	v_mul_f32_e32 v54, v53, v68
	v_mul_f32_e32 v54, 0xbfb8aa3b, v54
	v_exp_f32_e32 v58, v54
	ds_read_b128 v[54:57], v67 offset:10240
	ds_read_b128 v[74:77], v67 offset:10256
	ds_read_b128 v[78:81], v67 offset:12288
	s_waitcnt lgkmcnt(3)
	v_mul_f32_e32 v70, v53, v52
	ds_read_b128 v[82:85], v67 offset:10272
	ds_read_b128 v[86:89], v67 offset:10288
	v_pk_mul_f32 v[24:25], v[24:25], v[58:59] op_sel_hi:[1,0]
	v_pk_mul_f32 v[26:27], v[26:27], v[58:59] op_sel_hi:[1,0]
	s_waitcnt lgkmcnt(4)
	v_pk_fma_f32 v[24:25], v[56:57], v[70:71], v[24:25] op_sel_hi:[1,0,1]
	v_pk_fma_f32 v[26:27], v[54:55], v[70:71], v[26:27] op_sel_hi:[1,0,1]
	ds_read_b128 v[54:57], v67 offset:12304
	s_waitcnt lgkmcnt(3)
	v_mul_f32_e32 v59, v81, v25
	v_fmac_f32_e32 v59, v80, v24
	v_pk_mul_f32 v[28:29], v[28:29], v[58:59] op_sel_hi:[1,0]
	v_pk_mul_f32 v[30:31], v[30:31], v[58:59] op_sel_hi:[1,0]
	v_pk_fma_f32 v[28:29], v[70:71], v[76:77], v[28:29] op_sel_hi:[0,1,1]
	v_pk_fma_f32 v[30:31], v[70:71], v[74:75], v[30:31] op_sel_hi:[0,1,1]
	s_waitcnt lgkmcnt(2)
	v_pk_mul_f32 v[74:75], v[70:71], v[84:85] op_sel_hi:[0,1]
	v_pk_mul_f32 v[76:77], v[70:71], v[82:83] op_sel_hi:[0,1]
	v_mul_f32_e32 v53, v79, v27
	v_pk_fma_f32 v[22:23], v[22:23], v[58:59], v[74:75] op_sel_hi:[1,0,1]
	v_pk_fma_f32 v[20:21], v[20:21], v[58:59], v[76:77] op_sel_hi:[1,0,1]
	ds_read_b128 v[74:77], v67 offset:12336
	s_waitcnt lgkmcnt(1)
	v_mul_f32_e32 v55, v55, v31
	v_fmac_f32_e32 v53, v78, v26
	v_fmac_f32_e32 v55, v54, v30
	v_mul_f32_e32 v54, v57, v29
	v_add_f32_e32 v53, v53, v59
	v_fmac_f32_e32 v54, v56, v28
	v_add_f32_e32 v53, 0, v53
	v_add_f32_e32 v54, v55, v54
	v_add_f32_e32 v53, v54, v53
	ds_read_b128 v[54:57], v67 offset:12320
	s_waitcnt lgkmcnt(0)
	v_mul_f32_e32 v55, v55, v21
	v_fmac_f32_e32 v55, v54, v20
	v_mul_f32_e32 v54, v57, v23
	v_fmac_f32_e32 v54, v56, v22
	v_add_f32_e32 v54, v55, v54
	v_add_f32_e32 v53, v54, v53
	v_pk_mul_f32 v[54:55], v[70:71], v[88:89] op_sel_hi:[0,1]
	v_pk_mul_f32 v[56:57], v[70:71], v[86:87] op_sel_hi:[0,1]
	v_pk_fma_f32 v[18:19], v[18:19], v[58:59], v[54:55] op_sel_hi:[1,0,1]
	v_pk_fma_f32 v[16:17], v[16:17], v[58:59], v[56:57] op_sel_hi:[1,0,1]
	v_mul_f32_e32 v55, v77, v19
	v_mul_f32_e32 v54, v75, v17
	v_fmac_f32_e32 v54, v74, v16
	v_fmac_f32_e32 v55, v76, v18
	v_add_f32_e32 v54, v54, v55
	v_add_f32_e32 v53, v53, v54
	ds_bpermute_b32 v54, v61, v53
	s_waitcnt lgkmcnt(0)
	v_add_f32_e32 v53, v53, v54
	ds_bpermute_b32 v54, v62, v53
	s_waitcnt lgkmcnt(0)
	v_add_f32_e32 v53, v53, v54
	ds_bpermute_b32 v54, v63, v53
	s_and_saveexec_b64 s[14:15], s[6:7]
	s_cbranch_execz .Lssd2_691
	ds_read_b32 v55, v64 offset:44288
	s_waitcnt lgkmcnt(1)
	v_add_f32_e32 v53, v53, v54
	v_fmac_f32_e32 v53, v66, v52
	s_waitcnt lgkmcnt(0)
	v_mul_f32_e32 v56, 0xbfb8aa3b, v55
	v_exp_f32_e32 v56, v56
	s_nop 0
	v_add_f32_e32 v54, 1.0, v56
	v_div_scale_f32 v56, s[2:3], v54, v54, v55
	v_rcp_f32_e32 v57, v56
	v_div_scale_f32 v52, vcc, v55, v54, v55
	v_fma_f32 v58, -v56, v57, 1.0
	v_fmac_f32_e32 v57, v58, v57
	v_mul_f32_e32 v58, v52, v57
	v_fma_f32 v59, -v56, v58, v52
	v_fmac_f32_e32 v58, v59, v57
	v_fma_f32 v52, -v56, v58, v52
	v_div_fmas_f32 v52, v52, v57, v58
	v_div_fixup_f32 v52, v52, v54, v55
	v_mul_f32_e32 v52, v53, v52
	ds_write_b32 v64, v52 offset:32000
.Lssd2_691:
	s_or_b64 exec, exec, s[14:15]
	v_mov_b32_e32 v52, s1
	ds_read_b32 v56, v52 offset:96
	ds_read_b32 v69, v64 offset:14336
	s_waitcnt lgkmcnt(1)
	v_mul_f32_e32 v52, v56, v68
	v_mul_f32_e32 v52, 0xbfb8aa3b, v52
	v_exp_f32_e32 v70, v52
	ds_read_b128 v[52:55], v67 offset:17408
	ds_read_b128 v[74:77], v67 offset:17424
	ds_read_b128 v[78:81], v67 offset:19456
	s_waitcnt lgkmcnt(3)
	v_mul_f32_e32 v72, v56, v69
	v_pk_mul_f32 v[56:57], v[24:25], v[70:71] op_sel_hi:[1,0]
	v_pk_mul_f32 v[58:59], v[26:27], v[70:71] op_sel_hi:[1,0]
	s_waitcnt lgkmcnt(2)
	v_pk_fma_f32 v[56:57], v[54:55], v[72:73], v[56:57] op_sel_hi:[1,0,1]
	v_pk_fma_f32 v[58:59], v[52:53], v[72:73], v[58:59] op_sel_hi:[1,0,1]
	s_waitcnt lgkmcnt(0)
	v_mul_f32_e32 v53, v81, v57
	v_mul_f32_e32 v52, v79, v59
	ds_read_b128 v[24:27], v67 offset:17440
	ds_read_b128 v[82:85], v67 offset:17456
	ds_read_b128 v[86:89], v67 offset:19472
	v_fmac_f32_e32 v52, v78, v58
	v_fmac_f32_e32 v53, v80, v56
	v_add_f32_e32 v52, v52, v53
	v_add_f32_e32 v71, 0, v52
	v_pk_mul_f32 v[28:29], v[28:29], v[70:71] op_sel_hi:[1,0]
	v_pk_mul_f32 v[52:53], v[30:31], v[70:71] op_sel_hi:[1,0]
	v_pk_fma_f32 v[30:31], v[72:73], v[76:77], v[28:29] op_sel_hi:[0,1,1]
	v_pk_fma_f32 v[54:55], v[72:73], v[74:75], v[52:53] op_sel_hi:[0,1,1]
	ds_read_b128 v[74:77], v67 offset:19488
	s_waitcnt lgkmcnt(1)
	v_mul_f32_e32 v28, v87, v55
	v_mul_f32_e32 v29, v89, v31
	v_fmac_f32_e32 v28, v86, v54
	v_fmac_f32_e32 v29, v88, v30
	v_add_f32_e32 v28, v28, v29
	v_add_f32_e32 v52, v28, v71
	v_pk_mul_f32 v[28:29], v[72:73], v[26:27] op_sel_hi:[0,1]
	v_pk_mul_f32 v[24:25], v[72:73], v[24:25] op_sel_hi:[0,1]
	v_pk_fma_f32 v[28:29], v[22:23], v[70:71], v[28:29] op_sel_hi:[1,0,1]
	v_pk_fma_f32 v[26:27], v[20:21], v[70:71], v[24:25] op_sel_hi:[1,0,1]
	ds_read_b128 v[20:23], v67 offset:19504
	s_waitcnt lgkmcnt(1)
	v_mul_f32_e32 v24, v75, v27
	v_mul_f32_e32 v25, v77, v29
	v_fmac_f32_e32 v24, v74, v26
	v_fmac_f32_e32 v25, v76, v28
	v_add_f32_e32 v24, v24, v25
	v_add_f32_e32 v71, v24, v52
	v_pk_mul_f32 v[24:25], v[72:73], v[84:85] op_sel_hi:[0,1]
	v_pk_mul_f32 v[52:53], v[72:73], v[82:83] op_sel_hi:[0,1]
	v_pk_fma_f32 v[24:25], v[18:19], v[70:71], v[24:25] op_sel_hi:[1,0,1]
	v_pk_fma_f32 v[52:53], v[16:17], v[70:71], v[52:53] op_sel_hi:[1,0,1]
	s_waitcnt lgkmcnt(0)
	v_mul_f32_e32 v17, v23, v25
	v_mul_f32_e32 v16, v21, v53
	v_fmac_f32_e32 v16, v20, v52
	v_fmac_f32_e32 v17, v22, v24
	v_add_f32_e32 v16, v16, v17
	v_add_f32_e32 v16, v71, v16
	ds_bpermute_b32 v17, v61, v16
	s_waitcnt lgkmcnt(0)
	v_add_f32_e32 v16, v16, v17
	ds_bpermute_b32 v17, v62, v16
	s_waitcnt lgkmcnt(0)
	v_add_f32_e32 v16, v16, v17
	ds_bpermute_b32 v17, v63, v16
	s_and_saveexec_b64 s[14:15], s[6:7]
	s_cbranch_execz .Lssd2_693
	ds_read_b32 v18, v64 offset:47360
	s_waitcnt lgkmcnt(1)
	v_add_f32_e32 v16, v16, v17
	v_fmac_f32_e32 v16, v66, v69
	s_waitcnt lgkmcnt(0)
	v_mul_f32_e32 v19, 0xbfb8aa3b, v18
	v_exp_f32_e32 v19, v19
	s_nop 0
	v_add_f32_e32 v17, 1.0, v19
	v_div_scale_f32 v19, s[2:3], v17, v17, v18
	v_rcp_f32_e32 v20, v19
	v_div_scale_f32 v21, vcc, v18, v17, v18
	v_fma_f32 v22, -v19, v20, 1.0
	v_fmac_f32_e32 v20, v22, v20
	v_mul_f32_e32 v22, v21, v20
	v_fma_f32 v23, -v19, v22, v21
	v_fmac_f32_e32 v22, v23, v20
	v_fma_f32 v19, -v19, v22, v21
	v_div_fmas_f32 v19, v19, v20, v22
	v_div_fixup_f32 v17, v19, v17, v18
	v_mul_f32_e32 v16, v16, v17
	ds_write_b32 v64, v16 offset:35072
.Lssd2_693:
	s_or_b64 exec, exec, s[14:15]
	v_mov_b32_e32 v16, s1
	ds_read_b32 v70, v16 offset:144
	ds_read_b32 v69, v64 offset:21504
	s_waitcnt lgkmcnt(1)
	v_mul_f32_e32 v16, v70, v68
	v_mul_f32_e32 v16, 0xbfb8aa3b, v16
	v_exp_f32_e32 v68, v16
	ds_read_b128 v[16:19], v67 offset:24576
	ds_read_b128 v[20:23], v67 offset:24592
	ds_read_b128 v[74:77], v67 offset:26624
	s_waitcnt lgkmcnt(3)
	v_mul_f32_e32 v70, v70, v69
	v_pk_mul_f32 v[82:83], v[56:57], v[68:69] op_sel_hi:[1,0]
	v_pk_mul_f32 v[84:85], v[58:59], v[68:69] op_sel_hi:[1,0]
	s_waitcnt lgkmcnt(2)
	v_pk_fma_f32 v[18:19], v[18:19], v[70:71], v[82:83] op_sel_hi:[1,0,1]
	v_pk_fma_f32 v[16:17], v[16:17], v[70:71], v[84:85] op_sel_hi:[1,0,1]
	ds_read_b128 v[56:59], v67 offset:24608
	ds_read_b128 v[78:81], v67 offset:24624
	ds_read_b128 v[82:85], v67 offset:26640
	s_waitcnt lgkmcnt(3)
	v_mul_f32_e32 v71, v75, v17
	v_mul_f32_e32 v72, v77, v19
	v_fmac_f32_e32 v71, v74, v16
	v_fmac_f32_e32 v72, v76, v18
	v_add_f32_e32 v71, v71, v72
	v_add_f32_e32 v71, 0, v71
	v_pk_mul_f32 v[30:31], v[30:31], v[68:69] op_sel_hi:[1,0]
	v_pk_mul_f32 v[54:55], v[54:55], v[68:69] op_sel_hi:[1,0]
	v_pk_fma_f32 v[22:23], v[70:71], v[22:23], v[30:31] op_sel_hi:[0,1,1]
	v_pk_fma_f32 v[20:21], v[70:71], v[20:21], v[54:55] op_sel_hi:[0,1,1]
	ds_read_b128 v[74:77], v67 offset:26656
	s_waitcnt lgkmcnt(1)
	v_mul_f32_e32 v30, v83, v21
	v_mul_f32_e32 v31, v85, v23
	v_fmac_f32_e32 v30, v82, v20
	v_fmac_f32_e32 v31, v84, v22
	v_add_f32_e32 v30, v30, v31
	v_add_f32_e32 v71, v30, v71
	v_pk_mul_f32 v[30:31], v[70:71], v[58:59] op_sel_hi:[0,1]
	v_pk_mul_f32 v[54:55], v[70:71], v[56:57] op_sel_hi:[0,1]
	v_pk_fma_f32 v[30:31], v[28:29], v[68:69], v[30:31] op_sel_hi:[1,0,1]
	v_pk_fma_f32 v[28:29], v[26:27], v[68:69], v[54:55] op_sel_hi:[1,0,1]
	ds_read_b128 v[54:57], v67 offset:26672
	s_waitcnt lgkmcnt(1)
	v_mul_f32_e32 v26, v75, v29
	v_mul_f32_e32 v27, v77, v31
	v_fmac_f32_e32 v26, v74, v28
	v_fmac_f32_e32 v27, v76, v30
	v_add_f32_e32 v26, v26, v27
	v_add_f32_e32 v67, v26, v71
	v_pk_mul_f32 v[26:27], v[70:71], v[80:81] op_sel_hi:[0,1]
	v_pk_mul_f32 v[58:59], v[70:71], v[78:79] op_sel_hi:[0,1]
	v_pk_fma_f32 v[26:27], v[24:25], v[68:69], v[26:27] op_sel_hi:[1,0,1]
	v_pk_fma_f32 v[24:25], v[52:53], v[68:69], v[58:59] op_sel_hi:[1,0,1]
	s_waitcnt lgkmcnt(0)
	v_mul_f32_e32 v53, v57, v27
	v_mul_f32_e32 v52, v55, v25
	v_fmac_f32_e32 v52, v54, v24
	v_fmac_f32_e32 v53, v56, v26
	v_add_f32_e32 v52, v52, v53
	v_add_f32_e32 v52, v67, v52
	ds_bpermute_b32 v53, v61, v52
	s_waitcnt lgkmcnt(0)
	v_add_f32_e32 v52, v52, v53
	ds_bpermute_b32 v53, v62, v52
	s_waitcnt lgkmcnt(0)
	v_add_f32_e32 v52, v52, v53
	ds_bpermute_b32 v53, v63, v52
	s_and_saveexec_b64 s[14:15], s[6:7]
	s_cbranch_execz .Lssd2_tail
	ds_read_b32 v54, v64 offset:50432
	s_waitcnt lgkmcnt(1)
	v_add_f32_e32 v52, v52, v53
	v_fmac_f32_e32 v52, v66, v69
	s_waitcnt lgkmcnt(0)
	v_mul_f32_e32 v55, 0xbfb8aa3b, v54
	v_exp_f32_e32 v55, v55
	s_nop 0
	v_add_f32_e32 v53, 1.0, v55
	v_div_scale_f32 v55, s[2:3], v53, v53, v54
	v_rcp_f32_e32 v56, v55
	v_div_scale_f32 v57, vcc, v54, v53, v54
	v_fma_f32 v58, -v55, v56, 1.0
	v_fmac_f32_e32 v56, v58, v56
	v_mul_f32_e32 v58, v57, v56
	v_fma_f32 v59, -v55, v58, v57
	v_fmac_f32_e32 v58, v59, v56
	v_fma_f32 v55, -v55, v58, v57
	v_div_fmas_f32 v55, v55, v56, v58
	v_div_fixup_f32 v53, v55, v53, v54
	v_mul_f32_e32 v52, v52, v53
	ds_write_b32 v64, v52 offset:38144
	s_branch .Lssd2_tail
.Lssd2_tail:
	s_or_b64 exec, exec, s[14:15]
	s_add_i32 s0, s0, 1
	s_add_i32 s1, s1, 4
	s_waitcnt lgkmcnt(0)
	v_lshl_add_u64 v[52:53], v[50:51], 0, s[8:9]
	s_add_u32 s8, s8, 0x8000
	s_addc_u32 s9, s9, 0
	v_add_co_u32_e32 v52, vcc, 0x2fb35000, v52
	s_add_u32 s12, s12, 4
	s_nop 0
	v_addc_co_u32_e32 v53, vcc, 0, v53, vcc
	s_addc_u32 s13, s13, 0
	global_store_dwordx4 v[52:53], v[16:19], off nt
	global_store_dwordx4 v[52:53], v[20:23], off offset:16 nt
	global_store_dwordx4 v[52:53], v[28:31], off offset:32 nt
	global_store_dwordx4 v[52:53], v[24:27], off offset:48 nt
	s_add_u32 s10, s10, 4
	s_addc_u32 s11, s11, 0
	v_add_u32_e32 v64, 0x100, v64
	s_cmp_eq_u32 s8, 0x60000
	s_cbranch_scc1 .LBB0_695
	s_branch .Lssd_body0
